# variant: non-temporal stores on every bf16 GEMM output (GZ/GQP too), for comparison with the GM1-only version
# speedup vs baseline: 1.0406x; 1.0119x over previous
; DI void normmod_phase(const float* xl, const float* xc, const float* g, const float* modl  , int cshift, int cscale, bf16_t* H, int nrows, int gw, int NGW, int lane,
;                       const float* part  , const float* pgate  , float* xc_out) {
;     auto ld = [&](const int row, f32x4 (&v)[4]) __attribute__((always_inline)) -> float {
;         const bool lat = row < ML;
;         const float* xr = lat ? xl + (size_t)row * D : xc + (size_t)(row - ML) * D;
;         float ss = 0.f;
; #pragma unroll
;         for (int j = 0; j < 4; ++j) { v[j] = *(const f32x4*)(xr + lane * 4 + 256 * j);
;             if (part && !lat) {
;                 const size_t po = (size_t)(row - ML) * D + lane * 4 + 256 * j;
;                 const f32x4 p0 = *(const f32x4*)(part + po), p1 = *(const f32x4*)(part + (size_t)MC * D + po), p2 = *(const f32x4*)(part + (size_t)2 * MC * D + po), p3 = *(const f32x4*)(part + (size_t)3 * MC * D + po);
;                 v[j] = v[j] + *(const f32x4*)(pgate + lane * 4 + 256 * j) * ((p0 + p1) + (p2 + p3));
;                 *(f32x4*)(xc_out + po) = v[j]; }
;             ss += (v[j][0] * v[j][0] + v[j][1] * v[j][1]) + (v[j][2] * v[j][2] + v[j][3] * v[j][3]); }
;         return ss; };
;     auto st = [&](const int row, const f32x4 (&v)[4], const float rs) __attribute__((always_inline)) {
;         const float* mp = modl + (size_t)((row < ML) ? (row >> 12) : 16) * 6144;
; #pragma unroll
;         for (int j = 0; j < 4; ++j) { const int c = lane * 4 + 256 * j;
;             const f32x4 gg = *(const f32x4*)(g + c), sh = *(const f32x4*)(mp + cshift * 1024 + c), scl = *(const f32x4*)(mp + cscale * 1024 + c);
;             const f32x4 y = (v[j] * rs) * gg * (scl + 1.f) + sh;
;             u32x2 o; o.x = pk2(y[0], y[1]); o.y = pk2(y[2], y[3]);
;             *(u32x2*)(H + (size_t)row * D + c) = o; } };
;     for (int row = gw * 4; row < (nrows < ML ? nrows : ML); row += NGW * 4) {
;         f32x4 vA[4], vB[4], vC[4], vD[4];
;         float sA = ld(row, vA), sB = ld(row + 1, vB), sC = ld(row + 2, vC), sD = ld(row + 3, vD);
; #pragma unroll
;         for (int o = 1; o < 64; o <<= 1) { sA += __shfl_xor(sA, o); sB += __shfl_xor(sB, o); sC += __shfl_xor(sC, o); sD += __shfl_xor(sD, o); }
;         st(row, vA, rsqrtf(sA * (1.f / D) + EPS)); st(row + 1, vB, rsqrtf(sB * (1.f / D) + EPS));
.LBB0_314:
	s_lshl_b32 s8, s69, 12
	s_add_u32 s4, s4, s8
	s_addc_u32 s5, s5, 0
	s_add_u32 s8, s84, 0x312dc000
	v_readlane_b32 s56, v253, 23
	s_addc_u32 s9, s85, 0
	v_readlane_b32 s57, v253, 24
	s_and_b64 s[26:27], s[56:57], exec
	s_cselect_b32 s25, 0, s8
	s_cselect_b32 s20, 0, s9
	s_add_u32 s38, s25, 0x1000000
	s_addc_u32 s39, s20, 0
	s_add_u32 s40, s25, 0x2000000
	s_addc_u32 s41, s20, 0
	s_add_u32 s42, s25, 0x3000000
	v_lshlrev_b32_e32 v69, 2, v152
	v_lshlrev_b32_e32 v74, 4, v152
	v_mov_b32_e32 v75, v149
	s_addc_u32 s43, s20, 0
	v_lshl_add_u64 v[0:1], s[16:17], 0, v[74:75]
	s_mov_b64 s[26:27], 0x62000
	v_or_b32_e32 v68, 0x100, v69
	v_or_b32_e32 v70, 0x200, v69
	v_or_b32_e32 v72, 0x300, v69
	s_cmpk_gt_i32 s36, 0x3fff
	v_lshl_add_u64 v[64:65], v[0:1], 0, s[26:27]
	v_lshl_add_u64 v[66:67], s[4:5], 0, v[74:75]
	v_lshlrev_b32_e32 v71, 2, v68
	v_lshlrev_b32_e32 v73, 2, v70
	v_lshlrev_b32_e32 v80, 2, v72
	s_cbranch_scc1 .LBB0_353
	v_xor_b32_e32 v0, 1, v210
	v_cmp_lt_i32_e32 vcc, v0, v250
	s_lshl_b32 s5, s96, 5
	s_lshl_b32 s20, s37, 2
	v_cndmask_b32_e32 v0, v210, v0, vcc
	v_lshlrev_b32_e32 v81, 2, v0
	v_xor_b32_e32 v0, 2, v210
	v_cmp_lt_i32_e32 vcc, v0, v250
	s_lshl_b32 s4, s36, 2
	s_add_i32 s5, s5, s20
	v_cndmask_b32_e32 v0, v210, v0, vcc
	v_cmp_lt_i32_e32 vcc, v251, v250
	v_lshlrev_b32_e32 v82, 2, v0
	s_add_i32 s20, s5, 0xffff0001
	v_cndmask_b32_e32 v0, v210, v251, vcc
	v_lshlrev_b32_e32 v83, 2, v0
	v_xor_b32_e32 v0, 8, v210
	s_ashr_i32 s5, s4, 31
	s_lshl_b32 s26, s33, 5
	v_cmp_lt_i32_e32 vcc, v0, v250
	s_lshl_b64 s[30:31], s[4:5], 12
	s_add_u32 s44, s10, s30
	v_cndmask_b32_e32 v0, v210, v0, vcc
	v_lshlrev_b32_e32 v84, 2, v0
	v_xor_b32_e32 v0, 16, v210
	s_addc_u32 s45, s11, s31
	s_ashr_i32 s27, s26, 31
	v_cmp_lt_i32_e32 vcc, v0, v250
	s_lshl_b64 s[46:47], s[26:27], 12
	s_lshl_b64 s[4:5], s[4:5], 11
	v_readlane_b32 s12, v254, 26
	v_cndmask_b32_e32 v0, v210, v0, vcc
	s_add_u32 s25, s12, s78
	v_readlane_b32 s12, v254, 27
	v_lshlrev_b32_e32 v85, 2, v0
	v_xor_b32_e32 v0, 32, v210
	s_addc_u32 s30, s12, s79
	v_cmp_lt_i32_e32 vcc, v0, v250
	s_add_u32 s4, s25, s4
	v_lshlrev_b32_e32 v148, 3, v152
	v_cndmask_b32_e32 v0, v210, v0, vcc
	s_addc_u32 s5, s30, s5
	v_lshlrev_b32_e32 v86, 2, v0
	v_lshl_add_u64 v[76:77], s[4:5], 0, v[148:149]
	s_lshl_b64 s[48:49], s[26:27], 11
	global_load_dwordx4 v[156:159], v[66:67], off
	global_load_dwordx4 v[160:163], v[66:67], off offset:1024
	global_load_dwordx4 v[164:167], v[66:67], off offset:2048
	global_load_dwordx4 v[168:171], v[66:67], off offset:3072
	s_add_u32 s4, s44, 0x1000
	s_addc_u32 s5, s45, 0
	s_add_u32 s34, s44, 0x2000
	s_addc_u32 s35, s45, 0
	s_add_u32 s54, s44, 0x3000
	s_addc_u32 s55, s45, 0
	global_load_dwordx4 v[0:3], v74, s[44:45] nt
	global_load_dwordx4 v[4:7], v74, s[44:45] offset:1024 nt
	global_load_dwordx4 v[8:11], v74, s[44:45] offset:2048 nt
	global_load_dwordx4 v[12:15], v74, s[44:45] offset:3072 nt
	global_load_dwordx4 v[16:19], v74, s[4:5] nt
	global_load_dwordx4 v[20:23], v74, s[4:5] offset:1024 nt
	global_load_dwordx4 v[24:27], v74, s[4:5] offset:2048 nt
	global_load_dwordx4 v[28:31], v74, s[4:5] offset:3072 nt
	global_load_dwordx4 v[32:35], v74, s[34:35] nt
	global_load_dwordx4 v[36:39], v74, s[34:35] offset:1024 nt
	global_load_dwordx4 v[40:43], v74, s[34:35] offset:2048 nt
	global_load_dwordx4 v[44:47], v74, s[34:35] offset:3072 nt
	global_load_dwordx4 v[48:51], v74, s[54:55] nt
	global_load_dwordx4 v[52:55], v74, s[54:55] offset:1024 nt
	global_load_dwordx4 v[56:59], v74, s[54:55] offset:2048 nt
	global_load_dwordx4 v[60:63], v74, s[54:55] offset:3072 nt
	s_branch .LBB0_317
.LBB0_317:
	s_add_i32 s30, s20, 0xffff
	s_ashr_i32 s30, s30, 12
	s_mul_hi_i32 s31, s30, 0x6000
	s_mulk_i32 s30, 0x6000
	s_add_u32 s50, s16, s30
	s_addc_u32 s51, s17, s31
	s_add_u32 s50, s50, 0x3000
	s_addc_u32 s51, s51, 0
	s_add_u32 s52, s50, 0x1000
	s_addc_u32 s53, s51, 0
	global_load_dwordx4 v[110:113], v74, s[50:51]
	global_load_dwordx4 v[114:117], v74, s[50:51] offset:1024
	global_load_dwordx4 v[118:121], v74, s[50:51] offset:2048
	global_load_dwordx4 v[122:125], v74, s[50:51] offset:3072
	global_load_dwordx4 v[126:129], v74, s[52:53]
	global_load_dwordx4 v[130:133], v74, s[52:53] offset:1024
	global_load_dwordx4 v[134:137], v74, s[52:53] offset:2048
	global_load_dwordx4 v[138:141], v74, s[52:53] offset:3072
	s_add_i32 s27, s20, s26
	s_add_i32 s27, s27, 0xffff
	s_cmp_gt_i32 s27, 0xffff
	s_cselect_b32 s30, 0, s46
	s_cselect_b32 s31, 0, s47
	s_add_u32 s44, s44, s30
	s_addc_u32 s45, s45, s31
	s_add_u32 s4, s44, 0x1000
	s_addc_u32 s5, s45, 0
	s_add_u32 s34, s44, 0x2000
	s_addc_u32 s35, s45, 0
	s_add_u32 s54, s44, 0x3000
	s_addc_u32 s55, s45, 0
	s_mov_b32 s30, 0xfffff000
	s_mov_b32 s31, -1
	v_mov_b32_e32 v178, s68
	v_lshl_add_u64 v[198:199], v[76:77], 0, s[30:31]
	s_waitcnt vmcnt(20)
	v_mul_f32_e32 v176, v1, v1
	v_mul_f32_e32 v177, v3, v3
	v_fmac_f32_e32 v176, v0, v0
	v_fmac_f32_e32 v177, v2, v2
	v_add_f32_e32 v172, v176, v177
	v_mul_f32_e32 v176, v5, v5
	v_mul_f32_e32 v177, v7, v7
	v_fmac_f32_e32 v176, v4, v4
	v_fmac_f32_e32 v177, v6, v6
	v_add_f32_e32 v176, v176, v177
	v_add_f32_e32 v172, v172, v176
	v_mul_f32_e32 v176, v9, v9
	v_mul_f32_e32 v177, v11, v11
	v_fmac_f32_e32 v176, v8, v8
	v_fmac_f32_e32 v177, v10, v10
	v_add_f32_e32 v176, v176, v177
	v_add_f32_e32 v172, v172, v176
	v_mul_f32_e32 v176, v13, v13
	v_mul_f32_e32 v177, v15, v15
	v_fmac_f32_e32 v176, v12, v12
	v_fmac_f32_e32 v177, v14, v14
	v_add_f32_e32 v176, v176, v177
	v_add_f32_e32 v172, v172, v176
	s_waitcnt vmcnt(16)
; DI unsigned pk2(float lo, float hi) { f32x2 v = {lo, hi}; bf16x2_t b = __builtin_convertvector(v, bf16x2_t); return __builtin_bit_cast(unsigned, b); }
; DI void normmod_phase(const float* xl, const float* xc, const float* g, const float* modl  , int cshift, int cscale, bf16_t* H, int nrows, int gw, int NGW, int lane,
;                       const float* part  , const float* pgate  , float* xc_out) {
;     ...
;         for (int j = 0; j < 4; ++j) { v[j] = *(const f32x4*)(xr + lane * 4 + 256 * j);
;             if (part && !lat) {
;                 const size_t po = (size_t)(row - ML) * D + lane * 4 + 256 * j;
;                 const f32x4 p0 = *(const f32x4*)(part + po), p1 = *(const f32x4*)(part + (size_t)MC * D + po), p2 = *(const f32x4*)(part + (size_t)2 * MC * D + po), p3 = *(const f32x4*)(part + (size_t)3 * MC * D + po);
;                 v[j] = v[j] + *(const f32x4*)(pgate + lane * 4 + 256 * j) * ((p0 + p1) + (p2 + p3));
;                 *(f32x4*)(xc_out + po) = v[j]; }
;             ss += (v[j][0] * v[j][0] + v[j][1] * v[j][1]) + (v[j][2] * v[j][2] + v[j][3] * v[j][3]); }
;         return ss; };
;     auto st = [&](const int row, const f32x4 (&v)[4], const float rs) __attribute__((always_inline)) {
;         const float* mp = modl + (size_t)((row < ML) ? (row >> 12) : 16) * 6144;
; #pragma unroll
;         for (int j = 0; j < 4; ++j) { const int c = lane * 4 + 256 * j;
;             const f32x4 gg = *(const f32x4*)(g + c), sh = *(const f32x4*)(mp + cshift * 1024 + c), scl = *(const f32x4*)(mp + cscale * 1024 + c);
;             const f32x4 y = (v[j] * rs) * gg * (scl + 1.f) + sh;
;             u32x2 o; o.x = pk2(y[0], y[1]); o.y = pk2(y[2], y[3]);
;             *(u32x2*)(H + (size_t)row * D + c) = o; } };
;     for (int row = gw * 4; row < (nrows < ML ? nrows : ML); row += NGW * 4) {
;         f32x4 vA[4], vB[4], vC[4], vD[4];
;         float sA = ld(row, vA), sB = ld(row + 1, vB), sC = ld(row + 2, vC), sD = ld(row + 3, vD);
; #pragma unroll
;         for (int o = 1; o < 64; o <<= 1) { sA += __shfl_xor(sA, o); sB += __shfl_xor(sB, o); sC += __shfl_xor(sC, o); sD += __shfl_xor(sD, o); }
;         st(row, vA, rsqrtf(sA * (1.f / D) + EPS)); st(row + 1, vB, rsqrtf(sB * (1.f / D) + EPS));
	v_mul_f32_e32 v176, v17, v17
	v_mul_f32_e32 v177, v19, v19
	v_fmac_f32_e32 v176, v16, v16
	v_fmac_f32_e32 v177, v18, v18
	v_add_f32_e32 v173, v176, v177
	v_mul_f32_e32 v176, v21, v21
	v_mul_f32_e32 v177, v23, v23
	v_fmac_f32_e32 v176, v20, v20
	v_fmac_f32_e32 v177, v22, v22
	v_add_f32_e32 v176, v176, v177
	v_add_f32_e32 v173, v173, v176
	v_mul_f32_e32 v176, v25, v25
	v_mul_f32_e32 v177, v27, v27
	v_fmac_f32_e32 v176, v24, v24
	v_fmac_f32_e32 v177, v26, v26
	v_add_f32_e32 v176, v176, v177
	v_add_f32_e32 v173, v173, v176
	v_mul_f32_e32 v176, v29, v29
	v_mul_f32_e32 v177, v31, v31
	v_fmac_f32_e32 v176, v28, v28
	v_fmac_f32_e32 v177, v30, v30
	v_add_f32_e32 v176, v176, v177
	v_add_f32_e32 v173, v173, v176
	s_waitcnt vmcnt(12)
	v_mul_f32_e32 v176, v33, v33
	v_mul_f32_e32 v177, v35, v35
	v_fmac_f32_e32 v176, v32, v32
	v_fmac_f32_e32 v177, v34, v34
	v_add_f32_e32 v174, v176, v177
	v_mul_f32_e32 v176, v37, v37
	v_mul_f32_e32 v177, v39, v39
	v_fmac_f32_e32 v176, v36, v36
	v_fmac_f32_e32 v177, v38, v38
	v_add_f32_e32 v176, v176, v177
	v_add_f32_e32 v174, v174, v176
	v_mul_f32_e32 v176, v41, v41
	v_mul_f32_e32 v177, v43, v43
	v_fmac_f32_e32 v176, v40, v40
	v_fmac_f32_e32 v177, v42, v42
	v_add_f32_e32 v176, v176, v177
	v_add_f32_e32 v174, v174, v176
	v_mul_f32_e32 v176, v45, v45
	v_mul_f32_e32 v177, v47, v47
	v_fmac_f32_e32 v176, v44, v44
	v_fmac_f32_e32 v177, v46, v46
	v_add_f32_e32 v176, v176, v177
	v_add_f32_e32 v174, v174, v176
	s_waitcnt vmcnt(8)
	v_mul_f32_e32 v176, v49, v49
	v_mul_f32_e32 v177, v51, v51
	v_fmac_f32_e32 v176, v48, v48
	v_fmac_f32_e32 v177, v50, v50
	v_add_f32_e32 v175, v176, v177
	v_mul_f32_e32 v176, v53, v53
	v_mul_f32_e32 v177, v55, v55
	v_fmac_f32_e32 v176, v52, v52
	v_fmac_f32_e32 v177, v54, v54
	v_add_f32_e32 v176, v176, v177
	v_add_f32_e32 v175, v175, v176
	v_mul_f32_e32 v176, v57, v57
	v_mul_f32_e32 v177, v59, v59
	v_fmac_f32_e32 v176, v56, v56
	v_fmac_f32_e32 v177, v58, v58
	v_add_f32_e32 v176, v176, v177
	v_add_f32_e32 v175, v175, v176
	v_mul_f32_e32 v176, v61, v61
	v_mul_f32_e32 v177, v63, v63
	v_fmac_f32_e32 v176, v60, v60
	v_fmac_f32_e32 v177, v62, v62
	v_add_f32_e32 v176, v176, v177
	v_add_f32_e32 v175, v175, v176
	ds_bpermute_b32 v184, v81, v172
	ds_bpermute_b32 v185, v81, v173
	ds_bpermute_b32 v186, v81, v174
	ds_bpermute_b32 v187, v81, v175
	s_waitcnt lgkmcnt(0)
	v_pk_add_f32 v[172:173], v[172:173], v[184:185]
	v_pk_add_f32 v[174:175], v[174:175], v[186:187]
	ds_bpermute_b32 v184, v82, v172
	ds_bpermute_b32 v185, v82, v173
	ds_bpermute_b32 v186, v82, v174
	ds_bpermute_b32 v187, v82, v175
	s_waitcnt lgkmcnt(0)
	v_pk_add_f32 v[172:173], v[172:173], v[184:185]
	v_pk_add_f32 v[174:175], v[174:175], v[186:187]
	ds_bpermute_b32 v184, v83, v172
	ds_bpermute_b32 v185, v83, v173
	ds_bpermute_b32 v186, v83, v174
	ds_bpermute_b32 v187, v83, v175
	s_waitcnt lgkmcnt(0)
	v_pk_add_f32 v[172:173], v[172:173], v[184:185]
	v_pk_add_f32 v[174:175], v[174:175], v[186:187]
	ds_bpermute_b32 v184, v84, v172
	ds_bpermute_b32 v185, v84, v173
	ds_bpermute_b32 v186, v84, v174
	ds_bpermute_b32 v187, v84, v175
	s_waitcnt lgkmcnt(0)
	v_pk_add_f32 v[172:173], v[172:173], v[184:185]
	v_pk_add_f32 v[174:175], v[174:175], v[186:187]
	ds_bpermute_b32 v184, v85, v172
	ds_bpermute_b32 v185, v85, v173
	ds_bpermute_b32 v186, v85, v174
	ds_bpermute_b32 v187, v85, v175
	s_waitcnt lgkmcnt(0)
	v_pk_add_f32 v[172:173], v[172:173], v[184:185]
	v_pk_add_f32 v[174:175], v[174:175], v[186:187]
	ds_bpermute_b32 v184, v86, v172
	ds_bpermute_b32 v185, v86, v173
	ds_bpermute_b32 v186, v86, v174
	ds_bpermute_b32 v187, v86, v175
	s_waitcnt lgkmcnt(0)
	v_pk_add_f32 v[172:173], v[172:173], v[184:185]
	v_pk_add_f32 v[174:175], v[174:175], v[186:187]
	v_fma_f32 v172, v172, s66, v178
	v_fma_f32 v173, v173, s66, v178
	v_fma_f32 v174, v174, s66, v178
	v_fma_f32 v175, v175, s66, v178
	v_mul_f32_e32 v184, 0x4b800000, v172
	v_mul_f32_e32 v185, 0x4b800000, v173
	v_mul_f32_e32 v186, 0x4b800000, v174
	v_mul_f32_e32 v187, 0x4b800000, v175
	s_waitcnt vmcnt(0)
	v_cmp_gt_f32_e64 s[50:51], s62, v172
	v_cmp_gt_f32_e64 s[52:53], s62, v173
	v_cmp_gt_f32_e64 s[30:31], s62, v174
	v_cmp_gt_f32_e32 vcc, s62, v175
	s_nop 1
	v_cndmask_b32_e64 v172, v172, v184, s[50:51]
	v_cndmask_b32_e64 v173, v173, v185, s[52:53]
	v_cndmask_b32_e64 v174, v174, v186, s[30:31]
	v_cndmask_b32_e32 v175, v175, v187, vcc
	v_rsq_f32_e32 v172, v172
	v_rsq_f32_e32 v173, v173
	v_rsq_f32_e32 v174, v174
	v_rsq_f32_e32 v175, v175
	s_nop 0
	v_mul_f32_e32 v184, 0x45800000, v172
	v_mul_f32_e32 v185, 0x45800000, v173
	v_mul_f32_e32 v186, 0x45800000, v174
	v_mul_f32_e32 v187, 0x45800000, v175
	v_cndmask_b32_e64 v188, v172, v184, s[50:51]
	v_cndmask_b32_e64 v190, v173, v185, s[52:53]
	v_cndmask_b32_e64 v192, v174, v186, s[30:31]
	v_cndmask_b32_e32 v194, v175, v187, vcc
	v_pk_add_f32 v[126:127], v[126:127], 1.0 op_sel_hi:[1,0]
	v_pk_add_f32 v[128:129], v[128:129], 1.0 op_sel_hi:[1,0]
	v_pk_add_f32 v[130:131], v[130:131], 1.0 op_sel_hi:[1,0]
	v_pk_add_f32 v[132:133], v[132:133], 1.0 op_sel_hi:[1,0]
	v_pk_add_f32 v[134:135], v[134:135], 1.0 op_sel_hi:[1,0]
	v_pk_add_f32 v[136:137], v[136:137], 1.0 op_sel_hi:[1,0]
	v_pk_add_f32 v[138:139], v[138:139], 1.0 op_sel_hi:[1,0]
	v_pk_add_f32 v[140:141], v[140:141], 1.0 op_sel_hi:[1,0]
	v_pk_mul_f32 v[0:1], v[0:1], v[188:189] op_sel_hi:[1,0]
	v_pk_mul_f32 v[2:3], v[2:3], v[188:189] op_sel_hi:[1,0]
	v_pk_mul_f32 v[0:1], v[156:157], v[0:1]
	v_pk_mul_f32 v[2:3], v[158:159], v[2:3]
	v_pk_fma_f32 v[0:1], v[126:127], v[0:1], v[110:111]
	v_pk_fma_f32 v[2:3], v[128:129], v[2:3], v[112:113]
	v_cvt_pk_bf16_f32 v0, v0, v1
	v_cvt_pk_bf16_f32 v1, v2, v3
	global_store_dwordx2 v[198:199], v[0:1], off offset:-3584
; DI unsigned pk2(float lo, float hi) { f32x2 v = {lo, hi}; bf16x2_t b = __builtin_convertvector(v, bf16x2_t); return __builtin_bit_cast(unsigned, b); }
; DI void normmod_phase(const float* xl, const float* xc, const float* g, const float* modl  , int cshift, int cscale, bf16_t* H, int nrows, int gw, int NGW, int lane,
;                       const float* part  , const float* pgate  , float* xc_out) {
;     ...
;     auto st = [&](const int row, const f32x4 (&v)[4], const float rs) __attribute__((always_inline)) {
;         const float* mp = modl + (size_t)((row < ML) ? (row >> 12) : 16) * 6144;
; #pragma unroll
;         for (int j = 0; j < 4; ++j) { const int c = lane * 4 + 256 * j;
;             const f32x4 gg = *(const f32x4*)(g + c), sh = *(const f32x4*)(mp + cshift * 1024 + c), scl = *(const f32x4*)(mp + cscale * 1024 + c);
;             const f32x4 y = (v[j] * rs) * gg * (scl + 1.f) + sh;
;             u32x2 o; o.x = pk2(y[0], y[1]); o.y = pk2(y[2], y[3]);
;             *(u32x2*)(H + (size_t)row * D + c) = o; } };
;     for (int row = gw * 4; row < (nrows < ML ? nrows : ML); row += NGW * 4) {
	v_pk_mul_f32 v[4:5], v[4:5], v[188:189] op_sel_hi:[1,0]
	v_pk_mul_f32 v[6:7], v[6:7], v[188:189] op_sel_hi:[1,0]
	v_pk_mul_f32 v[4:5], v[160:161], v[4:5]
	v_pk_mul_f32 v[6:7], v[162:163], v[6:7]
	v_pk_fma_f32 v[4:5], v[130:131], v[4:5], v[114:115]
	v_pk_fma_f32 v[6:7], v[132:133], v[6:7], v[116:117]
	v_cvt_pk_bf16_f32 v4, v4, v5
	v_cvt_pk_bf16_f32 v5, v6, v7
	global_store_dwordx2 v[198:199], v[4:5], off offset:-3072
	v_pk_mul_f32 v[8:9], v[8:9], v[188:189] op_sel_hi:[1,0]
	v_pk_mul_f32 v[10:11], v[10:11], v[188:189] op_sel_hi:[1,0]
	v_pk_mul_f32 v[8:9], v[164:165], v[8:9]
	v_pk_mul_f32 v[10:11], v[166:167], v[10:11]
	v_pk_fma_f32 v[8:9], v[134:135], v[8:9], v[118:119]
	v_pk_fma_f32 v[10:11], v[136:137], v[10:11], v[120:121]
	v_cvt_pk_bf16_f32 v8, v8, v9
	v_cvt_pk_bf16_f32 v9, v10, v11
	global_store_dwordx2 v[198:199], v[8:9], off offset:-2560
	v_pk_mul_f32 v[12:13], v[12:13], v[188:189] op_sel_hi:[1,0]
	v_pk_mul_f32 v[14:15], v[14:15], v[188:189] op_sel_hi:[1,0]
	v_pk_mul_f32 v[12:13], v[168:169], v[12:13]
	v_pk_mul_f32 v[14:15], v[170:171], v[14:15]
	v_pk_fma_f32 v[12:13], v[138:139], v[12:13], v[122:123]
	v_pk_fma_f32 v[14:15], v[140:141], v[14:15], v[124:125]
	v_cvt_pk_bf16_f32 v12, v12, v13
	v_cvt_pk_bf16_f32 v13, v14, v15
	global_store_dwordx2 v[198:199], v[12:13], off offset:-2048
	global_load_dwordx4 v[0:3], v74, s[44:45] nt
	global_load_dwordx4 v[4:7], v74, s[44:45] offset:1024 nt
	global_load_dwordx4 v[8:11], v74, s[44:45] offset:2048 nt
	global_load_dwordx4 v[12:15], v74, s[44:45] offset:3072 nt
	v_pk_mul_f32 v[16:17], v[16:17], v[190:191] op_sel_hi:[1,0]
	v_pk_mul_f32 v[18:19], v[18:19], v[190:191] op_sel_hi:[1,0]
	v_pk_mul_f32 v[16:17], v[156:157], v[16:17]
	v_pk_mul_f32 v[18:19], v[158:159], v[18:19]
	v_pk_fma_f32 v[16:17], v[126:127], v[16:17], v[110:111]
	v_pk_fma_f32 v[18:19], v[128:129], v[18:19], v[112:113]
	v_cvt_pk_bf16_f32 v16, v16, v17
	v_cvt_pk_bf16_f32 v17, v18, v19
	global_store_dwordx2 v[198:199], v[16:17], off offset:-1536
	v_pk_mul_f32 v[20:21], v[20:21], v[190:191] op_sel_hi:[1,0]
	v_pk_mul_f32 v[22:23], v[22:23], v[190:191] op_sel_hi:[1,0]
	v_pk_mul_f32 v[20:21], v[160:161], v[20:21]
	v_pk_mul_f32 v[22:23], v[162:163], v[22:23]
	v_pk_fma_f32 v[20:21], v[130:131], v[20:21], v[114:115]
	v_pk_fma_f32 v[22:23], v[132:133], v[22:23], v[116:117]
	v_cvt_pk_bf16_f32 v20, v20, v21
	v_cvt_pk_bf16_f32 v21, v22, v23
	global_store_dwordx2 v[198:199], v[20:21], off offset:-1024
	v_pk_mul_f32 v[24:25], v[24:25], v[190:191] op_sel_hi:[1,0]
	v_pk_mul_f32 v[26:27], v[26:27], v[190:191] op_sel_hi:[1,0]
	v_pk_mul_f32 v[24:25], v[164:165], v[24:25]
	v_pk_mul_f32 v[26:27], v[166:167], v[26:27]
	v_pk_fma_f32 v[24:25], v[134:135], v[24:25], v[118:119]
	v_pk_fma_f32 v[26:27], v[136:137], v[26:27], v[120:121]
	v_cvt_pk_bf16_f32 v24, v24, v25
	v_cvt_pk_bf16_f32 v25, v26, v27
	global_store_dwordx2 v[198:199], v[24:25], off offset:-512
	v_pk_mul_f32 v[28:29], v[28:29], v[190:191] op_sel_hi:[1,0]
	v_pk_mul_f32 v[30:31], v[30:31], v[190:191] op_sel_hi:[1,0]
	v_pk_mul_f32 v[28:29], v[168:169], v[28:29]
	v_pk_mul_f32 v[30:31], v[170:171], v[30:31]
	v_pk_fma_f32 v[28:29], v[138:139], v[28:29], v[122:123]
	v_pk_fma_f32 v[30:31], v[140:141], v[30:31], v[124:125]
	v_cvt_pk_bf16_f32 v28, v28, v29
	v_cvt_pk_bf16_f32 v29, v30, v31
	global_store_dwordx2 v[76:77], v[28:29], off offset:-4096
	global_load_dwordx4 v[16:19], v74, s[4:5] nt
	global_load_dwordx4 v[20:23], v74, s[4:5] offset:1024 nt
	global_load_dwordx4 v[24:27], v74, s[4:5] offset:2048 nt
	global_load_dwordx4 v[28:31], v74, s[4:5] offset:3072 nt
	v_pk_mul_f32 v[32:33], v[32:33], v[192:193] op_sel_hi:[1,0]
	v_pk_mul_f32 v[34:35], v[34:35], v[192:193] op_sel_hi:[1,0]
	v_pk_mul_f32 v[32:33], v[156:157], v[32:33]
	v_pk_mul_f32 v[34:35], v[158:159], v[34:35]
	v_pk_fma_f32 v[32:33], v[126:127], v[32:33], v[110:111]
	v_pk_fma_f32 v[34:35], v[128:129], v[34:35], v[112:113]
; DI unsigned pk2(float lo, float hi) { f32x2 v = {lo, hi}; bf16x2_t b = __builtin_convertvector(v, bf16x2_t); return __builtin_bit_cast(unsigned, b); }
; DI void normmod_phase(const float* xl, const float* xc, const float* g, const float* modl  , int cshift, int cscale, bf16_t* H, int nrows, int gw, int NGW, int lane,
;                       const float* part  , const float* pgate  , float* xc_out) {
;     ...
;     auto st = [&](const int row, const f32x4 (&v)[4], const float rs) __attribute__((always_inline)) {
;         const float* mp = modl + (size_t)((row < ML) ? (row >> 12) : 16) * 6144;
; #pragma unroll
;         for (int j = 0; j < 4; ++j) { const int c = lane * 4 + 256 * j;
;             const f32x4 gg = *(const f32x4*)(g + c), sh = *(const f32x4*)(mp + cshift * 1024 + c), scl = *(const f32x4*)(mp + cscale * 1024 + c);
;             const f32x4 y = (v[j] * rs) * gg * (scl + 1.f) + sh;
;             u32x2 o; o.x = pk2(y[0], y[1]); o.y = pk2(y[2], y[3]);
;             *(u32x2*)(H + (size_t)row * D + c) = o; } };
;     for (int row = gw * 4; row < (nrows < ML ? nrows : ML); row += NGW * 4) {
	v_cvt_pk_bf16_f32 v32, v32, v33
	v_cvt_pk_bf16_f32 v33, v34, v35
	global_store_dwordx2 v[76:77], v[32:33], off offset:-3584
	v_pk_mul_f32 v[36:37], v[36:37], v[192:193] op_sel_hi:[1,0]
	v_pk_mul_f32 v[38:39], v[38:39], v[192:193] op_sel_hi:[1,0]
	v_pk_mul_f32 v[36:37], v[160:161], v[36:37]
	v_pk_mul_f32 v[38:39], v[162:163], v[38:39]
	v_pk_fma_f32 v[36:37], v[130:131], v[36:37], v[114:115]
	v_pk_fma_f32 v[38:39], v[132:133], v[38:39], v[116:117]
	v_cvt_pk_bf16_f32 v36, v36, v37
	v_cvt_pk_bf16_f32 v37, v38, v39
	global_store_dwordx2 v[76:77], v[36:37], off offset:-3072
	v_pk_mul_f32 v[40:41], v[40:41], v[192:193] op_sel_hi:[1,0]
	v_pk_mul_f32 v[42:43], v[42:43], v[192:193] op_sel_hi:[1,0]
	v_pk_mul_f32 v[40:41], v[164:165], v[40:41]
	v_pk_mul_f32 v[42:43], v[166:167], v[42:43]
	v_pk_fma_f32 v[40:41], v[134:135], v[40:41], v[118:119]
	v_pk_fma_f32 v[42:43], v[136:137], v[42:43], v[120:121]
	v_cvt_pk_bf16_f32 v40, v40, v41
	v_cvt_pk_bf16_f32 v41, v42, v43
	global_store_dwordx2 v[76:77], v[40:41], off offset:-2560
	v_pk_mul_f32 v[44:45], v[44:45], v[192:193] op_sel_hi:[1,0]
	v_pk_mul_f32 v[46:47], v[46:47], v[192:193] op_sel_hi:[1,0]
	v_pk_mul_f32 v[44:45], v[168:169], v[44:45]
	v_pk_mul_f32 v[46:47], v[170:171], v[46:47]
	v_pk_fma_f32 v[44:45], v[138:139], v[44:45], v[122:123]
	v_pk_fma_f32 v[46:47], v[140:141], v[46:47], v[124:125]
	v_cvt_pk_bf16_f32 v44, v44, v45
	v_cvt_pk_bf16_f32 v45, v46, v47
	global_store_dwordx2 v[76:77], v[44:45], off offset:-2048
	global_load_dwordx4 v[32:35], v74, s[34:35] nt
	global_load_dwordx4 v[36:39], v74, s[34:35] offset:1024 nt
	global_load_dwordx4 v[40:43], v74, s[34:35] offset:2048 nt
	global_load_dwordx4 v[44:47], v74, s[34:35] offset:3072 nt
	v_pk_mul_f32 v[48:49], v[48:49], v[194:195] op_sel_hi:[1,0]
	v_pk_mul_f32 v[50:51], v[50:51], v[194:195] op_sel_hi:[1,0]
	v_pk_mul_f32 v[48:49], v[156:157], v[48:49]
	v_pk_mul_f32 v[50:51], v[158:159], v[50:51]
	v_pk_fma_f32 v[48:49], v[126:127], v[48:49], v[110:111]
	v_pk_fma_f32 v[50:51], v[128:129], v[50:51], v[112:113]
	v_cvt_pk_bf16_f32 v48, v48, v49
	v_cvt_pk_bf16_f32 v49, v50, v51
	global_store_dwordx2 v[76:77], v[48:49], off offset:-1536
	v_pk_mul_f32 v[52:53], v[52:53], v[194:195] op_sel_hi:[1,0]
	v_pk_mul_f32 v[54:55], v[54:55], v[194:195] op_sel_hi:[1,0]
	v_pk_mul_f32 v[52:53], v[160:161], v[52:53]
	v_pk_mul_f32 v[54:55], v[162:163], v[54:55]
	v_pk_fma_f32 v[52:53], v[130:131], v[52:53], v[114:115]
	v_pk_fma_f32 v[54:55], v[132:133], v[54:55], v[116:117]
	v_cvt_pk_bf16_f32 v52, v52, v53
	v_cvt_pk_bf16_f32 v53, v54, v55
	global_store_dwordx2 v[76:77], v[52:53], off offset:-1024
	v_pk_mul_f32 v[56:57], v[56:57], v[194:195] op_sel_hi:[1,0]
	v_pk_mul_f32 v[58:59], v[58:59], v[194:195] op_sel_hi:[1,0]
	v_pk_mul_f32 v[56:57], v[164:165], v[56:57]
	v_pk_mul_f32 v[58:59], v[166:167], v[58:59]
	v_pk_fma_f32 v[56:57], v[134:135], v[56:57], v[118:119]
	v_pk_fma_f32 v[58:59], v[136:137], v[58:59], v[120:121]
	v_cvt_pk_bf16_f32 v56, v56, v57
	v_cvt_pk_bf16_f32 v57, v58, v59
	global_store_dwordx2 v[76:77], v[56:57], off offset:-512
	v_pk_mul_f32 v[60:61], v[60:61], v[194:195] op_sel_hi:[1,0]
	v_pk_mul_f32 v[62:63], v[62:63], v[194:195] op_sel_hi:[1,0]
	v_pk_mul_f32 v[60:61], v[168:169], v[60:61]
	v_pk_mul_f32 v[62:63], v[170:171], v[62:63]
	v_pk_fma_f32 v[60:61], v[138:139], v[60:61], v[122:123]
	v_pk_fma_f32 v[62:63], v[140:141], v[62:63], v[124:125]
	v_cvt_pk_bf16_f32 v60, v60, v61
	v_cvt_pk_bf16_f32 v61, v62, v63
	global_store_dwordx2 v[76:77], v[60:61], off
	global_load_dwordx4 v[48:51], v74, s[54:55] nt
	global_load_dwordx4 v[52:55], v74, s[54:55] offset:1024 nt
	global_load_dwordx4 v[56:59], v74, s[54:55] offset:2048 nt
	global_load_dwordx4 v[60:63], v74, s[54:55] offset:3072 nt
	s_add_i32 s20, s20, s26
	v_lshl_add_u64 v[76:77], v[76:77], 0, s[48:49]
	s_add_i32 s4, s20, 0xffff
	s_cmp_gt_i32 s4, 0xffff
	s_cbranch_scc0 .LBB0_317
	s_waitcnt vmcnt(0)

; DI void normmod_phase(const float* xl, const float* xc, const float* g, const float* modl  , int cshift, int cscale, bf16_t* H, int nrows, int gw, int NGW, int lane,
;                       const float* part  , const float* pgate  , float* xc_out) {
;     auto ld = [&](const int row, f32x4 (&v)[4]) __attribute__((always_inline)) -> float {
;         const bool lat = row < ML;
;         const float* xr = lat ? xl + (size_t)row * D : xc + (size_t)(row - ML) * D;
;         float ss = 0.f;
; #pragma unroll
;         for (int j = 0; j < 4; ++j) { v[j] = *(const f32x4*)(xr + lane * 4 + 256 * j);
;             if (part && !lat) {
;                 const size_t po = (size_t)(row - ML) * D + lane * 4 + 256 * j;
;                 const f32x4 p0 = *(const f32x4*)(part + po), p1 = *(const f32x4*)(part + (size_t)MC * D + po), p2 = *(const f32x4*)(part + (size_t)2 * MC * D + po), p3 = *(const f32x4*)(part + (size_t)3 * MC * D + po);
;                 v[j] = v[j] + *(const f32x4*)(pgate + lane * 4 + 256 * j) * ((p0 + p1) + (p2 + p3));
;                 *(f32x4*)(xc_out + po) = v[j]; }
;             ss += (v[j][0] * v[j][0] + v[j][1] * v[j][1]) + (v[j][2] * v[j][2] + v[j][3] * v[j][3]); }
;         return ss; };
;     auto st = [&](const int row, const f32x4 (&v)[4], const float rs) __attribute__((always_inline)) {
;         const float* mp = modl + (size_t)((row < ML) ? (row >> 12) : 16) * 6144;
; #pragma unroll
;         for (int j = 0; j < 4; ++j) { const int c = lane * 4 + 256 * j;
;             const f32x4 gg = *(const f32x4*)(g + c), sh = *(const f32x4*)(mp + cshift * 1024 + c), scl = *(const f32x4*)(mp + cscale * 1024 + c);
;             const f32x4 y = (v[j] * rs) * gg * (scl + 1.f) + sh;
;             u32x2 o; o.x = pk2(y[0], y[1]); o.y = pk2(y[2], y[3]);
;             *(u32x2*)(H + (size_t)row * D + c) = o; } };
;     for (int row = gw * 4; row < (nrows < ML ? nrows : ML); row += NGW * 4) {
;         f32x4 vA[4], vB[4], vC[4], vD[4];
;         float sA = ld(row, vA), sB = ld(row + 1, vB), sC = ld(row + 2, vC), sD = ld(row + 3, vD);
; #pragma unroll
;         for (int o = 1; o < 64; o <<= 1) { sA += __shfl_xor(sA, o); sB += __shfl_xor(sB, o); sC += __shfl_xor(sC, o); sD += __shfl_xor(sD, o); }
;         st(row, vA, rsqrtf(sA * (1.f / D) + EPS)); st(row + 1, vB, rsqrtf(sB * (1.f / D) + EPS));
.LBB0_553:
	s_andn2_b64 vcc, exec, s[4:5]
	s_cbranch_vccnz .LBB0_621
	s_lshl_b64 s[4:5], s[78:79], 3
	v_readlane_b32 s6, v253, 5
	v_readlane_b32 s7, v253, 6
	s_add_u32 s4, s6, s4
	s_addc_u32 s5, s7, s5
	s_load_dwordx2 s[4:5], s[4:5], 0x30
	s_lshl_b32 s6, s69, 12
	v_readlane_b32 s54, v253, 28
	v_readlane_b32 s55, v253, 29
	v_lshlrev_b32_e32 v69, 2, v152
	s_waitcnt lgkmcnt(0)
	s_add_u32 s4, s4, s6
	v_readlane_b32 s6, v253, 23
	s_addc_u32 s5, s5, 0
	v_readlane_b32 s7, v253, 24
	s_and_b64 s[6:7], s[6:7], exec
	s_cselect_b32 s23, 0, 0x15400000
	s_add_u32 s6, s84, 0x312dc000
	s_addc_u32 s7, s85, 0
	s_and_b64 s[8:9], s[54:55], exec
	s_cselect_b32 s24, 0, s6
	s_cselect_b32 s20, 0, s7
	s_add_u32 s8, s24, 0x1000000
	s_addc_u32 s9, s20, 0
	s_add_u32 s38, s24, 0x2000000
	s_addc_u32 s39, s20, 0
	s_add_u32 s40, s24, 0x3000000
	s_addc_u32 s41, s20, 0
	v_lshlrev_b32_e32 v76, 4, v152
	v_mov_b32_e32 v77, v149
	v_or_b32_e32 v68, 0x100, v69
	v_or_b32_e32 v70, 0x200, v69
	v_or_b32_e32 v72, 0x300, v69
	s_mov_b32 s56, s36
	s_cmpk_gt_i32 s36, 0x3fff
	v_lshl_add_u64 v[64:65], s[16:17], 0, v[76:77]
	v_lshl_add_u64 v[66:67], s[4:5], 0, v[76:77]
	v_lshlrev_b32_e32 v74, 3, v152
	v_lshlrev_b32_e32 v71, 2, v68
	v_lshlrev_b32_e32 v73, 2, v70
	v_lshlrev_b32_e32 v82, 2, v72
	s_movk_i32 s13, 0xf000
	s_mov_b32 s34, 0x3a800000
	s_mov_b32 s36, 0x358637bd
	s_cbranch_scc1 .LBB0_593
	s_waitcnt vmcnt(5)
	v_xor_b32_e32 v0, 1, v210
	v_cmp_lt_i32_e32 vcc, v0, v250
	s_lshl_b32 s5, s96, 5
	s_lshl_b32 s20, s37, 2
	v_cndmask_b32_e32 v0, v210, v0, vcc
	v_lshlrev_b32_e32 v83, 2, v0
	v_xor_b32_e32 v0, 2, v210
	s_lshl_b32 s4, s56, 2
	v_cmp_lt_i32_e32 vcc, v0, v250
	s_add_i32 s5, s5, s20
	s_add_i32 s20, s5, 0xffff0001
	v_cndmask_b32_e32 v0, v210, v0, vcc
	v_cmp_lt_i32_e32 vcc, v251, v250
	s_ashr_i32 s5, s4, 31
	s_lshl_b32 s26, s33, 5
	v_lshlrev_b32_e32 v84, 2, v0
	v_cndmask_b32_e32 v0, v210, v251, vcc
	s_lshl_b64 s[24:25], s[4:5], 12
	v_lshlrev_b32_e32 v85, 2, v0
	v_xor_b32_e32 v0, 8, v210
	s_add_u32 s42, s10, s24
	v_cmp_lt_i32_e32 vcc, v0, v250
	s_addc_u32 s43, s11, s25
	s_ashr_i32 s27, s26, 31
	v_cndmask_b32_e32 v0, v210, v0, vcc
	s_lshl_b64 s[44:45], s[26:27], 12
	s_lshl_b64 s[4:5], s[4:5], 11
	v_lshlrev_b32_e32 v86, 2, v0
	v_xor_b32_e32 v0, 16, v210
	s_add_u32 s4, s23, s4
	v_cmp_lt_i32_e32 vcc, v0, v250
	s_addc_u32 s5, 0, s5
	v_readlane_b32 s12, v254, 26
	v_cndmask_b32_e32 v0, v210, v0, vcc
	s_add_u32 s24, s12, s78
	v_readlane_b32 s12, v254, 27
	v_lshlrev_b32_e32 v87, 2, v0
	v_xor_b32_e32 v0, 32, v210
	s_addc_u32 s25, s12, s79
	v_cmp_lt_i32_e32 vcc, v0, v250
	s_add_u32 s4, s24, s4
	v_mov_b32_e32 v75, v149
	v_cndmask_b32_e32 v0, v210, v0, vcc
	s_addc_u32 s5, s25, s5
	v_lshlrev_b32_e32 v88, 2, v0
	v_lshl_add_u64 v[78:79], s[4:5], 0, v[74:75]
	s_lshl_b64 s[46:47], s[26:27], 11
	global_load_dwordx4 v[156:159], v[66:67], off
	global_load_dwordx4 v[160:163], v[66:67], off offset:1024
	global_load_dwordx4 v[164:167], v[66:67], off offset:2048
	global_load_dwordx4 v[168:171], v[66:67], off offset:3072
	s_add_u32 s4, s42, 0x1000
	s_addc_u32 s5, s43, 0
	s_add_u32 s24, s42, 0x2000
	s_addc_u32 s25, s43, 0
	s_add_u32 s48, s42, 0x3000
	s_addc_u32 s49, s43, 0
	global_load_dwordx4 v[0:3], v76, s[42:43] nt
	global_load_dwordx4 v[4:7], v76, s[42:43] offset:1024 nt
	global_load_dwordx4 v[8:11], v76, s[42:43] offset:2048 nt
	global_load_dwordx4 v[12:15], v76, s[42:43] offset:3072 nt
	global_load_dwordx4 v[16:19], v76, s[4:5] nt
	global_load_dwordx4 v[20:23], v76, s[4:5] offset:1024 nt
	global_load_dwordx4 v[24:27], v76, s[4:5] offset:2048 nt
	global_load_dwordx4 v[28:31], v76, s[4:5] offset:3072 nt
	global_load_dwordx4 v[32:35], v76, s[24:25] nt
	global_load_dwordx4 v[36:39], v76, s[24:25] offset:1024 nt
	global_load_dwordx4 v[40:43], v76, s[24:25] offset:2048 nt
	global_load_dwordx4 v[44:47], v76, s[24:25] offset:3072 nt
	global_load_dwordx4 v[48:51], v76, s[48:49] nt
	global_load_dwordx4 v[52:55], v76, s[48:49] offset:1024 nt
	global_load_dwordx4 v[56:59], v76, s[48:49] offset:2048 nt
	global_load_dwordx4 v[60:63], v76, s[48:49] offset:3072 nt
	s_branch .LBB0_557
.LBB0_557:
	s_add_i32 s30, s20, 0xffff
	s_ashr_i32 s30, s30, 12
	s_mul_hi_i32 s31, s30, 0x6000
	s_mulk_i32 s30, 0x6000
	s_add_u32 s50, s16, s30
	s_addc_u32 s51, s17, s31
	s_add_u32 s52, s50, 0x1000
	s_addc_u32 s53, s51, 0
	global_load_dwordx4 v[110:113], v76, s[50:51]
	global_load_dwordx4 v[114:117], v76, s[50:51] offset:1024
	global_load_dwordx4 v[118:121], v76, s[50:51] offset:2048
	global_load_dwordx4 v[122:125], v76, s[50:51] offset:3072
	global_load_dwordx4 v[126:129], v76, s[52:53]
	global_load_dwordx4 v[130:133], v76, s[52:53] offset:1024
	global_load_dwordx4 v[134:137], v76, s[52:53] offset:2048
	global_load_dwordx4 v[138:141], v76, s[52:53] offset:3072
	s_add_i32 s27, s20, s26
	s_add_i32 s27, s27, 0xffff
	s_cmp_gt_i32 s27, 0xffff
	s_cselect_b32 s30, 0, s44
	s_cselect_b32 s31, 0, s45
	s_add_u32 s42, s42, s30
	s_addc_u32 s43, s43, s31
	s_add_u32 s4, s42, 0x1000
	s_addc_u32 s5, s43, 0
	s_add_u32 s24, s42, 0x2000
	s_addc_u32 s25, s43, 0
	s_add_u32 s48, s42, 0x3000
	s_addc_u32 s49, s43, 0
	s_mov_b32 s30, 0xfffff000
	s_mov_b32 s31, -1
	v_mov_b32_e32 v178, s36
	v_lshl_add_u64 v[198:199], v[78:79], 0, s[30:31]
	s_waitcnt vmcnt(20)
	v_mul_f32_e32 v176, v1, v1
	v_mul_f32_e32 v177, v3, v3
	v_fmac_f32_e32 v176, v0, v0
	v_fmac_f32_e32 v177, v2, v2
	v_add_f32_e32 v172, v176, v177
	v_mul_f32_e32 v176, v5, v5
	v_mul_f32_e32 v177, v7, v7
	v_fmac_f32_e32 v176, v4, v4
	v_fmac_f32_e32 v177, v6, v6
	v_add_f32_e32 v176, v176, v177
	v_add_f32_e32 v172, v172, v176
	v_mul_f32_e32 v176, v9, v9
	v_mul_f32_e32 v177, v11, v11
	v_fmac_f32_e32 v176, v8, v8
	v_fmac_f32_e32 v177, v10, v10
	v_add_f32_e32 v176, v176, v177
	v_add_f32_e32 v172, v172, v176
	v_mul_f32_e32 v176, v13, v13
	v_mul_f32_e32 v177, v15, v15
	v_fmac_f32_e32 v176, v12, v12
	v_fmac_f32_e32 v177, v14, v14
	v_add_f32_e32 v176, v176, v177
	v_add_f32_e32 v172, v172, v176
	s_waitcnt vmcnt(16)
; DI unsigned pk2(float lo, float hi) { f32x2 v = {lo, hi}; bf16x2_t b = __builtin_convertvector(v, bf16x2_t); return __builtin_bit_cast(unsigned, b); }
; DI void normmod_phase(const float* xl, const float* xc, const float* g, const float* modl  , int cshift, int cscale, bf16_t* H, int nrows, int gw, int NGW, int lane,
;                       const float* part  , const float* pgate  , float* xc_out) {
;     ...
;         for (int j = 0; j < 4; ++j) { v[j] = *(const f32x4*)(xr + lane * 4 + 256 * j);
;             if (part && !lat) {
;                 const size_t po = (size_t)(row - ML) * D + lane * 4 + 256 * j;
;                 const f32x4 p0 = *(const f32x4*)(part + po), p1 = *(const f32x4*)(part + (size_t)MC * D + po), p2 = *(const f32x4*)(part + (size_t)2 * MC * D + po), p3 = *(const f32x4*)(part + (size_t)3 * MC * D + po);
;                 v[j] = v[j] + *(const f32x4*)(pgate + lane * 4 + 256 * j) * ((p0 + p1) + (p2 + p3));
;                 *(f32x4*)(xc_out + po) = v[j]; }
;             ss += (v[j][0] * v[j][0] + v[j][1] * v[j][1]) + (v[j][2] * v[j][2] + v[j][3] * v[j][3]); }
;         return ss; };
;     auto st = [&](const int row, const f32x4 (&v)[4], const float rs) __attribute__((always_inline)) {
;         const float* mp = modl + (size_t)((row < ML) ? (row >> 12) : 16) * 6144;
; #pragma unroll
;         for (int j = 0; j < 4; ++j) { const int c = lane * 4 + 256 * j;
;             const f32x4 gg = *(const f32x4*)(g + c), sh = *(const f32x4*)(mp + cshift * 1024 + c), scl = *(const f32x4*)(mp + cscale * 1024 + c);
;             const f32x4 y = (v[j] * rs) * gg * (scl + 1.f) + sh;
;             u32x2 o; o.x = pk2(y[0], y[1]); o.y = pk2(y[2], y[3]);
;             *(u32x2*)(H + (size_t)row * D + c) = o; } };
;     for (int row = gw * 4; row < (nrows < ML ? nrows : ML); row += NGW * 4) {
;         f32x4 vA[4], vB[4], vC[4], vD[4];
;         float sA = ld(row, vA), sB = ld(row + 1, vB), sC = ld(row + 2, vC), sD = ld(row + 3, vD);
; #pragma unroll
;         for (int o = 1; o < 64; o <<= 1) { sA += __shfl_xor(sA, o); sB += __shfl_xor(sB, o); sC += __shfl_xor(sC, o); sD += __shfl_xor(sD, o); }
;         st(row, vA, rsqrtf(sA * (1.f / D) + EPS)); st(row + 1, vB, rsqrtf(sB * (1.f / D) + EPS));
	v_mul_f32_e32 v176, v17, v17
	v_mul_f32_e32 v177, v19, v19
	v_fmac_f32_e32 v176, v16, v16
	v_fmac_f32_e32 v177, v18, v18
	v_add_f32_e32 v173, v176, v177
	v_mul_f32_e32 v176, v21, v21
	v_mul_f32_e32 v177, v23, v23
	v_fmac_f32_e32 v176, v20, v20
	v_fmac_f32_e32 v177, v22, v22
	v_add_f32_e32 v176, v176, v177
	v_add_f32_e32 v173, v173, v176
	v_mul_f32_e32 v176, v25, v25
	v_mul_f32_e32 v177, v27, v27
	v_fmac_f32_e32 v176, v24, v24
	v_fmac_f32_e32 v177, v26, v26
	v_add_f32_e32 v176, v176, v177
	v_add_f32_e32 v173, v173, v176
	v_mul_f32_e32 v176, v29, v29
	v_mul_f32_e32 v177, v31, v31
	v_fmac_f32_e32 v176, v28, v28
	v_fmac_f32_e32 v177, v30, v30
	v_add_f32_e32 v176, v176, v177
	v_add_f32_e32 v173, v173, v176
	s_waitcnt vmcnt(12)
	v_mul_f32_e32 v176, v33, v33
	v_mul_f32_e32 v177, v35, v35
	v_fmac_f32_e32 v176, v32, v32
	v_fmac_f32_e32 v177, v34, v34
	v_add_f32_e32 v174, v176, v177
	v_mul_f32_e32 v176, v37, v37
	v_mul_f32_e32 v177, v39, v39
	v_fmac_f32_e32 v176, v36, v36
	v_fmac_f32_e32 v177, v38, v38
	v_add_f32_e32 v176, v176, v177
	v_add_f32_e32 v174, v174, v176
	v_mul_f32_e32 v176, v41, v41
	v_mul_f32_e32 v177, v43, v43
	v_fmac_f32_e32 v176, v40, v40
	v_fmac_f32_e32 v177, v42, v42
	v_add_f32_e32 v176, v176, v177
	v_add_f32_e32 v174, v174, v176
	v_mul_f32_e32 v176, v45, v45
	v_mul_f32_e32 v177, v47, v47
	v_fmac_f32_e32 v176, v44, v44
	v_fmac_f32_e32 v177, v46, v46
	v_add_f32_e32 v176, v176, v177
	v_add_f32_e32 v174, v174, v176
	s_waitcnt vmcnt(8)
	v_mul_f32_e32 v176, v49, v49
	v_mul_f32_e32 v177, v51, v51
	v_fmac_f32_e32 v176, v48, v48
	v_fmac_f32_e32 v177, v50, v50
	v_add_f32_e32 v175, v176, v177
	v_mul_f32_e32 v176, v53, v53
	v_mul_f32_e32 v177, v55, v55
	v_fmac_f32_e32 v176, v52, v52
	v_fmac_f32_e32 v177, v54, v54
	v_add_f32_e32 v176, v176, v177
	v_add_f32_e32 v175, v175, v176
	v_mul_f32_e32 v176, v57, v57
	v_mul_f32_e32 v177, v59, v59
	v_fmac_f32_e32 v176, v56, v56
	v_fmac_f32_e32 v177, v58, v58
	v_add_f32_e32 v176, v176, v177
	v_add_f32_e32 v175, v175, v176
	v_mul_f32_e32 v176, v61, v61
	v_mul_f32_e32 v177, v63, v63
	v_fmac_f32_e32 v176, v60, v60
	v_fmac_f32_e32 v177, v62, v62
	v_add_f32_e32 v176, v176, v177
	v_add_f32_e32 v175, v175, v176
	ds_bpermute_b32 v184, v83, v172
	ds_bpermute_b32 v185, v83, v173
	ds_bpermute_b32 v186, v83, v174
	ds_bpermute_b32 v187, v83, v175
	s_waitcnt lgkmcnt(0)
	v_pk_add_f32 v[172:173], v[172:173], v[184:185]
	v_pk_add_f32 v[174:175], v[174:175], v[186:187]
	ds_bpermute_b32 v184, v84, v172
	ds_bpermute_b32 v185, v84, v173
	ds_bpermute_b32 v186, v84, v174
	ds_bpermute_b32 v187, v84, v175
	s_waitcnt lgkmcnt(0)
	v_pk_add_f32 v[172:173], v[172:173], v[184:185]
	v_pk_add_f32 v[174:175], v[174:175], v[186:187]
	ds_bpermute_b32 v184, v85, v172
	ds_bpermute_b32 v185, v85, v173
	ds_bpermute_b32 v186, v85, v174
	ds_bpermute_b32 v187, v85, v175
	s_waitcnt lgkmcnt(0)
	v_pk_add_f32 v[172:173], v[172:173], v[184:185]
	v_pk_add_f32 v[174:175], v[174:175], v[186:187]
	ds_bpermute_b32 v184, v86, v172
	ds_bpermute_b32 v185, v86, v173
	ds_bpermute_b32 v186, v86, v174
	ds_bpermute_b32 v187, v86, v175
	s_waitcnt lgkmcnt(0)
	v_pk_add_f32 v[172:173], v[172:173], v[184:185]
	v_pk_add_f32 v[174:175], v[174:175], v[186:187]
	ds_bpermute_b32 v184, v87, v172
	ds_bpermute_b32 v185, v87, v173
	ds_bpermute_b32 v186, v87, v174
	ds_bpermute_b32 v187, v87, v175
	s_waitcnt lgkmcnt(0)
	v_pk_add_f32 v[172:173], v[172:173], v[184:185]
	v_pk_add_f32 v[174:175], v[174:175], v[186:187]
	ds_bpermute_b32 v184, v88, v172
	ds_bpermute_b32 v185, v88, v173
	ds_bpermute_b32 v186, v88, v174
	ds_bpermute_b32 v187, v88, v175
	s_waitcnt lgkmcnt(0)
	v_pk_add_f32 v[172:173], v[172:173], v[184:185]
	v_pk_add_f32 v[174:175], v[174:175], v[186:187]
	v_fma_f32 v172, v172, s34, v178
	v_fma_f32 v173, v173, s34, v178
	v_fma_f32 v174, v174, s34, v178
	v_fma_f32 v175, v175, s34, v178
	v_mul_f32_e32 v184, 0x4b800000, v172
	v_mul_f32_e32 v185, 0x4b800000, v173
	v_mul_f32_e32 v186, 0x4b800000, v174
	v_mul_f32_e32 v187, 0x4b800000, v175
	s_waitcnt vmcnt(0)
	v_cmp_gt_f32_e64 s[50:51], s62, v172
	v_cmp_gt_f32_e64 s[52:53], s62, v173
	v_cmp_gt_f32_e64 s[30:31], s62, v174
	v_cmp_gt_f32_e32 vcc, s62, v175
	s_nop 1
	v_cndmask_b32_e64 v172, v172, v184, s[50:51]
	v_cndmask_b32_e64 v173, v173, v185, s[52:53]
	v_cndmask_b32_e64 v174, v174, v186, s[30:31]
	v_cndmask_b32_e32 v175, v175, v187, vcc
	v_rsq_f32_e32 v172, v172
	v_rsq_f32_e32 v173, v173
	v_rsq_f32_e32 v174, v174
	v_rsq_f32_e32 v175, v175
	s_nop 0
	v_mul_f32_e32 v184, 0x45800000, v172
	v_mul_f32_e32 v185, 0x45800000, v173
	v_mul_f32_e32 v186, 0x45800000, v174
	v_mul_f32_e32 v187, 0x45800000, v175
	v_cndmask_b32_e64 v188, v172, v184, s[50:51]
	v_cndmask_b32_e64 v190, v173, v185, s[52:53]
	v_cndmask_b32_e64 v192, v174, v186, s[30:31]
	v_cndmask_b32_e32 v194, v175, v187, vcc
	v_pk_add_f32 v[126:127], v[126:127], 1.0 op_sel_hi:[1,0]
	v_pk_add_f32 v[128:129], v[128:129], 1.0 op_sel_hi:[1,0]
	v_pk_add_f32 v[130:131], v[130:131], 1.0 op_sel_hi:[1,0]
	v_pk_add_f32 v[132:133], v[132:133], 1.0 op_sel_hi:[1,0]
	v_pk_add_f32 v[134:135], v[134:135], 1.0 op_sel_hi:[1,0]
	v_pk_add_f32 v[136:137], v[136:137], 1.0 op_sel_hi:[1,0]
	v_pk_add_f32 v[138:139], v[138:139], 1.0 op_sel_hi:[1,0]
	v_pk_add_f32 v[140:141], v[140:141], 1.0 op_sel_hi:[1,0]
	v_pk_mul_f32 v[0:1], v[0:1], v[188:189] op_sel_hi:[1,0]
	v_pk_mul_f32 v[2:3], v[2:3], v[188:189] op_sel_hi:[1,0]
	v_pk_mul_f32 v[0:1], v[156:157], v[0:1]
	v_pk_mul_f32 v[2:3], v[158:159], v[2:3]
	v_pk_fma_f32 v[0:1], v[126:127], v[0:1], v[110:111]
	v_pk_fma_f32 v[2:3], v[128:129], v[2:3], v[112:113]
	v_cvt_pk_bf16_f32 v0, v0, v1
	v_cvt_pk_bf16_f32 v1, v2, v3
	global_store_dwordx2 v[198:199], v[0:1], off offset:-3584
; DI unsigned pk2(float lo, float hi) { f32x2 v = {lo, hi}; bf16x2_t b = __builtin_convertvector(v, bf16x2_t); return __builtin_bit_cast(unsigned, b); }
; DI void normmod_phase(const float* xl, const float* xc, const float* g, const float* modl  , int cshift, int cscale, bf16_t* H, int nrows, int gw, int NGW, int lane,
;                       const float* part  , const float* pgate  , float* xc_out) {
;     ...
;     auto st = [&](const int row, const f32x4 (&v)[4], const float rs) __attribute__((always_inline)) {
;         const float* mp = modl + (size_t)((row < ML) ? (row >> 12) : 16) * 6144;
; #pragma unroll
;         for (int j = 0; j < 4; ++j) { const int c = lane * 4 + 256 * j;
;             const f32x4 gg = *(const f32x4*)(g + c), sh = *(const f32x4*)(mp + cshift * 1024 + c), scl = *(const f32x4*)(mp + cscale * 1024 + c);
;             const f32x4 y = (v[j] * rs) * gg * (scl + 1.f) + sh;
;             u32x2 o; o.x = pk2(y[0], y[1]); o.y = pk2(y[2], y[3]);
;             *(u32x2*)(H + (size_t)row * D + c) = o; } };
;     for (int row = gw * 4; row < (nrows < ML ? nrows : ML); row += NGW * 4) {
	v_pk_mul_f32 v[4:5], v[4:5], v[188:189] op_sel_hi:[1,0]
	v_pk_mul_f32 v[6:7], v[6:7], v[188:189] op_sel_hi:[1,0]
	v_pk_mul_f32 v[4:5], v[160:161], v[4:5]
	v_pk_mul_f32 v[6:7], v[162:163], v[6:7]
	v_pk_fma_f32 v[4:5], v[130:131], v[4:5], v[114:115]
	v_pk_fma_f32 v[6:7], v[132:133], v[6:7], v[116:117]
	v_cvt_pk_bf16_f32 v4, v4, v5
	v_cvt_pk_bf16_f32 v5, v6, v7
	global_store_dwordx2 v[198:199], v[4:5], off offset:-3072
	v_pk_mul_f32 v[8:9], v[8:9], v[188:189] op_sel_hi:[1,0]
	v_pk_mul_f32 v[10:11], v[10:11], v[188:189] op_sel_hi:[1,0]
	v_pk_mul_f32 v[8:9], v[164:165], v[8:9]
	v_pk_mul_f32 v[10:11], v[166:167], v[10:11]
	v_pk_fma_f32 v[8:9], v[134:135], v[8:9], v[118:119]
	v_pk_fma_f32 v[10:11], v[136:137], v[10:11], v[120:121]
	v_cvt_pk_bf16_f32 v8, v8, v9
	v_cvt_pk_bf16_f32 v9, v10, v11
	global_store_dwordx2 v[198:199], v[8:9], off offset:-2560
	v_pk_mul_f32 v[12:13], v[12:13], v[188:189] op_sel_hi:[1,0]
	v_pk_mul_f32 v[14:15], v[14:15], v[188:189] op_sel_hi:[1,0]
	v_pk_mul_f32 v[12:13], v[168:169], v[12:13]
	v_pk_mul_f32 v[14:15], v[170:171], v[14:15]
	v_pk_fma_f32 v[12:13], v[138:139], v[12:13], v[122:123]
	v_pk_fma_f32 v[14:15], v[140:141], v[14:15], v[124:125]
	v_cvt_pk_bf16_f32 v12, v12, v13
	v_cvt_pk_bf16_f32 v13, v14, v15
	global_store_dwordx2 v[198:199], v[12:13], off offset:-2048
	global_load_dwordx4 v[0:3], v76, s[42:43] nt
	global_load_dwordx4 v[4:7], v76, s[42:43] offset:1024 nt
	global_load_dwordx4 v[8:11], v76, s[42:43] offset:2048 nt
	global_load_dwordx4 v[12:15], v76, s[42:43] offset:3072 nt
	v_pk_mul_f32 v[16:17], v[16:17], v[190:191] op_sel_hi:[1,0]
	v_pk_mul_f32 v[18:19], v[18:19], v[190:191] op_sel_hi:[1,0]
	v_pk_mul_f32 v[16:17], v[156:157], v[16:17]
	v_pk_mul_f32 v[18:19], v[158:159], v[18:19]
	v_pk_fma_f32 v[16:17], v[126:127], v[16:17], v[110:111]
	v_pk_fma_f32 v[18:19], v[128:129], v[18:19], v[112:113]
	v_cvt_pk_bf16_f32 v16, v16, v17
	v_cvt_pk_bf16_f32 v17, v18, v19
	global_store_dwordx2 v[198:199], v[16:17], off offset:-1536
	v_pk_mul_f32 v[20:21], v[20:21], v[190:191] op_sel_hi:[1,0]
	v_pk_mul_f32 v[22:23], v[22:23], v[190:191] op_sel_hi:[1,0]
	v_pk_mul_f32 v[20:21], v[160:161], v[20:21]
	v_pk_mul_f32 v[22:23], v[162:163], v[22:23]
	v_pk_fma_f32 v[20:21], v[130:131], v[20:21], v[114:115]
	v_pk_fma_f32 v[22:23], v[132:133], v[22:23], v[116:117]
	v_cvt_pk_bf16_f32 v20, v20, v21
	v_cvt_pk_bf16_f32 v21, v22, v23
	global_store_dwordx2 v[198:199], v[20:21], off offset:-1024
	v_pk_mul_f32 v[24:25], v[24:25], v[190:191] op_sel_hi:[1,0]
	v_pk_mul_f32 v[26:27], v[26:27], v[190:191] op_sel_hi:[1,0]
	v_pk_mul_f32 v[24:25], v[164:165], v[24:25]
	v_pk_mul_f32 v[26:27], v[166:167], v[26:27]
	v_pk_fma_f32 v[24:25], v[134:135], v[24:25], v[118:119]
	v_pk_fma_f32 v[26:27], v[136:137], v[26:27], v[120:121]
	v_cvt_pk_bf16_f32 v24, v24, v25
	v_cvt_pk_bf16_f32 v25, v26, v27
	global_store_dwordx2 v[198:199], v[24:25], off offset:-512
	v_pk_mul_f32 v[28:29], v[28:29], v[190:191] op_sel_hi:[1,0]
	v_pk_mul_f32 v[30:31], v[30:31], v[190:191] op_sel_hi:[1,0]
	v_pk_mul_f32 v[28:29], v[168:169], v[28:29]
	v_pk_mul_f32 v[30:31], v[170:171], v[30:31]
	v_pk_fma_f32 v[28:29], v[138:139], v[28:29], v[122:123]
	v_pk_fma_f32 v[30:31], v[140:141], v[30:31], v[124:125]
	v_cvt_pk_bf16_f32 v28, v28, v29
	v_cvt_pk_bf16_f32 v29, v30, v31
	global_store_dwordx2 v[78:79], v[28:29], off offset:-4096
	global_load_dwordx4 v[16:19], v76, s[4:5] nt
	global_load_dwordx4 v[20:23], v76, s[4:5] offset:1024 nt
	global_load_dwordx4 v[24:27], v76, s[4:5] offset:2048 nt
	global_load_dwordx4 v[28:31], v76, s[4:5] offset:3072 nt
	v_pk_mul_f32 v[32:33], v[32:33], v[192:193] op_sel_hi:[1,0]
	v_pk_mul_f32 v[34:35], v[34:35], v[192:193] op_sel_hi:[1,0]
	v_pk_mul_f32 v[32:33], v[156:157], v[32:33]
	v_pk_mul_f32 v[34:35], v[158:159], v[34:35]
	v_pk_fma_f32 v[32:33], v[126:127], v[32:33], v[110:111]
	v_pk_fma_f32 v[34:35], v[128:129], v[34:35], v[112:113]
; DI unsigned pk2(float lo, float hi) { f32x2 v = {lo, hi}; bf16x2_t b = __builtin_convertvector(v, bf16x2_t); return __builtin_bit_cast(unsigned, b); }
; DI void normmod_phase(const float* xl, const float* xc, const float* g, const float* modl  , int cshift, int cscale, bf16_t* H, int nrows, int gw, int NGW, int lane,
;                       const float* part  , const float* pgate  , float* xc_out) {
;     ...
;     auto st = [&](const int row, const f32x4 (&v)[4], const float rs) __attribute__((always_inline)) {
;         const float* mp = modl + (size_t)((row < ML) ? (row >> 12) : 16) * 6144;
; #pragma unroll
;         for (int j = 0; j < 4; ++j) { const int c = lane * 4 + 256 * j;
;             const f32x4 gg = *(const f32x4*)(g + c), sh = *(const f32x4*)(mp + cshift * 1024 + c), scl = *(const f32x4*)(mp + cscale * 1024 + c);
;             const f32x4 y = (v[j] * rs) * gg * (scl + 1.f) + sh;
;             u32x2 o; o.x = pk2(y[0], y[1]); o.y = pk2(y[2], y[3]);
;             *(u32x2*)(H + (size_t)row * D + c) = o; } };
;     for (int row = gw * 4; row < (nrows < ML ? nrows : ML); row += NGW * 4) {
	v_cvt_pk_bf16_f32 v32, v32, v33
	v_cvt_pk_bf16_f32 v33, v34, v35
	global_store_dwordx2 v[78:79], v[32:33], off offset:-3584
	v_pk_mul_f32 v[36:37], v[36:37], v[192:193] op_sel_hi:[1,0]
	v_pk_mul_f32 v[38:39], v[38:39], v[192:193] op_sel_hi:[1,0]
	v_pk_mul_f32 v[36:37], v[160:161], v[36:37]
	v_pk_mul_f32 v[38:39], v[162:163], v[38:39]
	v_pk_fma_f32 v[36:37], v[130:131], v[36:37], v[114:115]
	v_pk_fma_f32 v[38:39], v[132:133], v[38:39], v[116:117]
	v_cvt_pk_bf16_f32 v36, v36, v37
	v_cvt_pk_bf16_f32 v37, v38, v39
	global_store_dwordx2 v[78:79], v[36:37], off offset:-3072
	v_pk_mul_f32 v[40:41], v[40:41], v[192:193] op_sel_hi:[1,0]
	v_pk_mul_f32 v[42:43], v[42:43], v[192:193] op_sel_hi:[1,0]
	v_pk_mul_f32 v[40:41], v[164:165], v[40:41]
	v_pk_mul_f32 v[42:43], v[166:167], v[42:43]
	v_pk_fma_f32 v[40:41], v[134:135], v[40:41], v[118:119]
	v_pk_fma_f32 v[42:43], v[136:137], v[42:43], v[120:121]
	v_cvt_pk_bf16_f32 v40, v40, v41
	v_cvt_pk_bf16_f32 v41, v42, v43
	global_store_dwordx2 v[78:79], v[40:41], off offset:-2560
	v_pk_mul_f32 v[44:45], v[44:45], v[192:193] op_sel_hi:[1,0]
	v_pk_mul_f32 v[46:47], v[46:47], v[192:193] op_sel_hi:[1,0]
	v_pk_mul_f32 v[44:45], v[168:169], v[44:45]
	v_pk_mul_f32 v[46:47], v[170:171], v[46:47]
	v_pk_fma_f32 v[44:45], v[138:139], v[44:45], v[122:123]
	v_pk_fma_f32 v[46:47], v[140:141], v[46:47], v[124:125]
	v_cvt_pk_bf16_f32 v44, v44, v45
	v_cvt_pk_bf16_f32 v45, v46, v47
	global_store_dwordx2 v[78:79], v[44:45], off offset:-2048
	global_load_dwordx4 v[32:35], v76, s[24:25] nt
	global_load_dwordx4 v[36:39], v76, s[24:25] offset:1024 nt
	global_load_dwordx4 v[40:43], v76, s[24:25] offset:2048 nt
	global_load_dwordx4 v[44:47], v76, s[24:25] offset:3072 nt
	v_pk_mul_f32 v[48:49], v[48:49], v[194:195] op_sel_hi:[1,0]
	v_pk_mul_f32 v[50:51], v[50:51], v[194:195] op_sel_hi:[1,0]
	v_pk_mul_f32 v[48:49], v[156:157], v[48:49]
	v_pk_mul_f32 v[50:51], v[158:159], v[50:51]
	v_pk_fma_f32 v[48:49], v[126:127], v[48:49], v[110:111]
	v_pk_fma_f32 v[50:51], v[128:129], v[50:51], v[112:113]
	v_cvt_pk_bf16_f32 v48, v48, v49
	v_cvt_pk_bf16_f32 v49, v50, v51
	global_store_dwordx2 v[78:79], v[48:49], off offset:-1536
	v_pk_mul_f32 v[52:53], v[52:53], v[194:195] op_sel_hi:[1,0]
	v_pk_mul_f32 v[54:55], v[54:55], v[194:195] op_sel_hi:[1,0]
	v_pk_mul_f32 v[52:53], v[160:161], v[52:53]
	v_pk_mul_f32 v[54:55], v[162:163], v[54:55]
	v_pk_fma_f32 v[52:53], v[130:131], v[52:53], v[114:115]
	v_pk_fma_f32 v[54:55], v[132:133], v[54:55], v[116:117]
	v_cvt_pk_bf16_f32 v52, v52, v53
	v_cvt_pk_bf16_f32 v53, v54, v55
	global_store_dwordx2 v[78:79], v[52:53], off offset:-1024
	v_pk_mul_f32 v[56:57], v[56:57], v[194:195] op_sel_hi:[1,0]
	v_pk_mul_f32 v[58:59], v[58:59], v[194:195] op_sel_hi:[1,0]
	v_pk_mul_f32 v[56:57], v[164:165], v[56:57]
	v_pk_mul_f32 v[58:59], v[166:167], v[58:59]
	v_pk_fma_f32 v[56:57], v[134:135], v[56:57], v[118:119]
	v_pk_fma_f32 v[58:59], v[136:137], v[58:59], v[120:121]
	v_cvt_pk_bf16_f32 v56, v56, v57
	v_cvt_pk_bf16_f32 v57, v58, v59
	global_store_dwordx2 v[78:79], v[56:57], off offset:-512
	v_pk_mul_f32 v[60:61], v[60:61], v[194:195] op_sel_hi:[1,0]
	v_pk_mul_f32 v[62:63], v[62:63], v[194:195] op_sel_hi:[1,0]
	v_pk_mul_f32 v[60:61], v[168:169], v[60:61]
	v_pk_mul_f32 v[62:63], v[170:171], v[62:63]
	v_pk_fma_f32 v[60:61], v[138:139], v[60:61], v[122:123]
	v_pk_fma_f32 v[62:63], v[140:141], v[62:63], v[124:125]
	v_cvt_pk_bf16_f32 v60, v60, v61
	v_cvt_pk_bf16_f32 v61, v62, v63
	global_store_dwordx2 v[78:79], v[60:61], off
	global_load_dwordx4 v[48:51], v76, s[48:49] nt
	global_load_dwordx4 v[52:55], v76, s[48:49] offset:1024 nt
	global_load_dwordx4 v[56:59], v76, s[48:49] offset:2048 nt
	global_load_dwordx4 v[60:63], v76, s[48:49] offset:3072 nt
	s_add_i32 s20, s20, s26
	v_lshl_add_u64 v[78:79], v[78:79], 0, s[46:47]
	s_add_i32 s4, s20, 0xffff
	s_cmp_gt_i32 s4, 0xffff
	s_cbranch_scc0 .LBB0_557
	s_waitcnt vmcnt(0)

;     DI void operator()(const f32x4 (&acc)[2][2][4][2], const Unit& u, int wr, int wc, int fr, int fq) const {
;         const int trow = u.pm * BM; const bool lat = trow < ML;
;         const float* src = lat ? src_l : src_c; float* dst = lat ? dst_l : dst_c;
;         const int rbase = (lat ? trow : trow - ML) + wr * 64 + fr; const int grow = lat ? (trow >> 12) : 16;
;         const float* gp = gate + (size_t)grow * 6144;
;         const int col0 = u.pn * BM + wc * 32 + 8 * fq;
; #pragma unroll
;         for (int bj = 0; bj < 2; ++bj) {
;             const int col = col0 + bj * HALF;
;             const f32x4 g0 = *(const f32x4*)(gp + col), g1 = *(const f32x4*)(gp + col + 4);
; #pragma unroll
;             for (int ai = 0; ai < 2; ++ai)
; #pragma unroll
;                 for (int m = 0; m < 4; ++m) { const size_t off = (size_t)(rbase + ai * HALF + m * 16) * D + col;
;                     const f32x4 x0 = *(const f32x4*)(src + off), x1 = *(const f32x4*)(src + off + 4);
;                     *(f32x4*)(dst + off) = x0 + g0 * acc[ai][bj][m][0]; *(f32x4*)(dst + off + 4) = x1 + g1 * acc[ai][bj][m][1]; }
;         }
;     }
.LBB0_701:
	s_lshl_b32 s12, s75, 8
	s_add_i32 s13, s12, 0xffff0000
	s_cmpk_lt_i32 s75, 0x100
	s_cselect_b32 s12, s12, s13
	s_cselect_b32 s69, s11, s15
	s_cselect_b32 s68, s10, s14
	s_cselect_b32 s27, s19, s3
	s_cselect_b32 s26, s18, s2
	s_min_i32 s34, s75, 0x100
	s_ashr_i32 s34, s34, 4
	s_mul_hi_i32 s35, s34, 0x6000
	s_mulk_i32 s34, 0x6000
	s_add_u32 s34, s79, s34
	s_addc_u32 s35, s80, s35
	v_and_b32_e32 v159, 15, v175
	v_lshrrev_b32_e32 v160, 6, v175
	v_bfe_u32 v161, v177, 3, 2
	v_lshrrev_b32_e32 v162, 5, v177
	v_lshl_add_u32 v163, v161, 4, v159
	v_lshl_add_u32 v154, v160, 2, v162
	v_mul_u32_u24_e32 v154, 0x900, v154
	v_add_u32_e32 v154, 0x21000, v154
	v_lshrrev_b32_e32 v157, 3, v163
	v_and_b32_e32 v158, 7, v163
	v_mul_u32_u24_e32 v155, 0x90, v157
	v_lshl_add_u32 v155, v158, 4, v155
	v_add_u32_e32 v155, v154, v155
	v_mul_u32_u24_e32 v156, 0x90, v159
	v_lshl_add_u32 v156, v161, 5, v156
	v_add_u32_e32 v154, v154, v156
	v_lshl_add_u32 v157, v160, 6, v157
	v_add_u32_e32 v157, s12, v157
	v_lshlrev_b32_e32 v158, 2, v158
	v_lshl_add_u32 v158, v162, 5, v158
	v_lshl_add_u32 v158, s31, 8, v158
	v_lshl_add_u32 v156, v157, 10, v158
	v_lshlrev_b32_e32 v156, 2, v156
	v_lshlrev_b32_e32 v158, 2, v158
	v_add_u32_e32 v157, 0x8000, v156
	global_load_dwordx4 v[128:131], v158, s[34:35]
	global_load_dwordx4 v[132:135], v158, s[34:35] offset:512
	global_load_dwordx4 v[180:183], v156, s[68:69]
	global_load_dwordx4 v[184:187], v156, s[68:69] offset:512
	global_load_dwordx4 v[188:191], v157, s[68:69]
	global_load_dwordx4 v[192:195], v157, s[68:69] offset:512
	s_add_u32 s68, s68, 0x10000
	s_addc_u32 s69, s69, 0
	global_load_dwordx4 v[196:199], v156, s[68:69]
	global_load_dwordx4 v[200:203], v156, s[68:69] offset:512
	global_load_dwordx4 v[204:207], v157, s[68:69]
	global_load_dwordx4 v[214:217], v157, s[68:69] offset:512
	s_add_u32 s68, s68, 0x10000
	s_addc_u32 s69, s69, 0
	global_load_dwordx4 v[218:221], v156, s[68:69]
	global_load_dwordx4 v[222:225], v156, s[68:69] offset:512
	global_load_dwordx4 v[226:229], v157, s[68:69]
	global_load_dwordx4 v[230:233], v157, s[68:69] offset:512
	s_add_u32 s68, s68, 0x10000
	s_addc_u32 s69, s69, 0
	ds_write_b128 v154, v[124:127]
	ds_write_b128 v154, v[120:123] offset:16
	ds_read_b128 v[124:127], v155
	ds_read_b128 v[120:123], v155 offset:1152
	ds_write_b128 v154, v[60:63]
	ds_write_b128 v154, v[56:59] offset:16
	ds_read_b128 v[60:63], v155
	ds_read_b128 v[56:59], v155 offset:1152
	ds_write_b128 v154, v[116:119]
	ds_write_b128 v154, v[112:115] offset:16
	ds_read_b128 v[116:119], v155
	ds_read_b128 v[112:115], v155 offset:1152
	ds_write_b128 v154, v[52:55]
	ds_write_b128 v154, v[48:51] offset:16
	ds_read_b128 v[52:55], v155
	ds_read_b128 v[48:51], v155 offset:1152
	s_waitcnt vmcnt(8) lgkmcnt(8)
	v_pk_fma_f32 v[124:125], v[124:125], v[128:129], v[180:181]
	v_pk_fma_f32 v[126:127], v[126:127], v[130:131], v[182:183]
	v_pk_fma_f32 v[60:61], v[60:61], v[132:133], v[184:185]
	v_pk_fma_f32 v[62:63], v[62:63], v[134:135], v[186:187]
	v_pk_fma_f32 v[120:121], v[120:121], v[128:129], v[188:189]
	v_pk_fma_f32 v[122:123], v[122:123], v[130:131], v[190:191]
	v_pk_fma_f32 v[56:57], v[56:57], v[132:133], v[192:193]
	v_pk_fma_f32 v[58:59], v[58:59], v[134:135], v[194:195]
	global_store_dwordx4 v156, v[124:127], s[26:27] nt
	global_store_dwordx4 v156, v[60:63], s[26:27] offset:512 nt
	global_store_dwordx4 v157, v[120:123], s[26:27] nt
	global_store_dwordx4 v157, v[56:59], s[26:27] offset:512 nt
	s_add_u32 s26, s26, 0x10000
	s_addc_u32 s27, s27, 0
	global_load_dwordx4 v[180:183], v156, s[68:69]
	global_load_dwordx4 v[184:187], v156, s[68:69] offset:512
	global_load_dwordx4 v[188:191], v157, s[68:69]
	global_load_dwordx4 v[192:195], v157, s[68:69] offset:512
	s_add_u32 s68, s68, 0x50000
	s_addc_u32 s69, s69, 0
	ds_write_b128 v154, v[108:111]
	ds_write_b128 v154, v[104:107] offset:16
	ds_read_b128 v[108:111], v155
	ds_read_b128 v[104:107], v155 offset:1152
	ds_write_b128 v154, v[44:47]
	ds_write_b128 v154, v[40:43] offset:16
	ds_read_b128 v[44:47], v155
	ds_read_b128 v[40:43], v155 offset:1152
	s_waitcnt vmcnt(12) lgkmcnt(8)
	v_pk_fma_f32 v[116:117], v[116:117], v[128:129], v[196:197]
	v_pk_fma_f32 v[118:119], v[118:119], v[130:131], v[198:199]
	v_pk_fma_f32 v[52:53], v[52:53], v[132:133], v[200:201]
	v_pk_fma_f32 v[54:55], v[54:55], v[134:135], v[202:203]
	v_pk_fma_f32 v[112:113], v[112:113], v[128:129], v[204:205]
	v_pk_fma_f32 v[114:115], v[114:115], v[130:131], v[206:207]
	v_pk_fma_f32 v[48:49], v[48:49], v[132:133], v[214:215]
	v_pk_fma_f32 v[50:51], v[50:51], v[134:135], v[216:217]
	global_store_dwordx4 v156, v[116:119], s[26:27] nt
	global_store_dwordx4 v156, v[52:55], s[26:27] offset:512 nt
	global_store_dwordx4 v157, v[112:115], s[26:27] nt
	global_store_dwordx4 v157, v[48:51], s[26:27] offset:512 nt
	s_add_u32 s26, s26, 0x10000
	s_addc_u32 s27, s27, 0
	global_load_dwordx4 v[196:199], v156, s[68:69]
	global_load_dwordx4 v[200:203], v156, s[68:69] offset:512
	global_load_dwordx4 v[204:207], v157, s[68:69]
	global_load_dwordx4 v[214:217], v157, s[68:69] offset:512
	s_add_u32 s68, s68, 0x10000
	s_addc_u32 s69, s69, 0
	ds_write_b128 v154, v[100:103]
	ds_write_b128 v154, v[96:99] offset:16
	ds_read_b128 v[100:103], v155
	ds_read_b128 v[96:99], v155 offset:1152
	ds_write_b128 v154, v[36:39]
	ds_write_b128 v154, v[32:35] offset:16
	ds_read_b128 v[36:39], v155
	ds_read_b128 v[32:35], v155 offset:1152
	s_waitcnt vmcnt(16) lgkmcnt(8)
;     DI void operator()(const f32x4 (&acc)[2][2][4][2], const Unit& u, int wr, int wc, int fr, int fq) const {
;         const int trow = u.pm * BM; const bool lat = trow < ML;
;         const float* src = lat ? src_l : src_c; float* dst = lat ? dst_l : dst_c;
;         const int rbase = (lat ? trow : trow - ML) + wr * 64 + fr; const int grow = lat ? (trow >> 12) : 16;
;         const float* gp = gate + (size_t)grow * 6144;
;         const int col0 = u.pn * BM + wc * 32 + 8 * fq;
; #pragma unroll
;         for (int bj = 0; bj < 2; ++bj) {
;             const int col = col0 + bj * HALF;
;             const f32x4 g0 = *(const f32x4*)(gp + col), g1 = *(const f32x4*)(gp + col + 4);
; #pragma unroll
;             for (int ai = 0; ai < 2; ++ai)
; #pragma unroll
;                 for (int m = 0; m < 4; ++m) { const size_t off = (size_t)(rbase + ai * HALF + m * 16) * D + col;
;                     const f32x4 x0 = *(const f32x4*)(src + off), x1 = *(const f32x4*)(src + off + 4);
;                     *(f32x4*)(dst + off) = x0 + g0 * acc[ai][bj][m][0]; *(f32x4*)(dst + off + 4) = x1 + g1 * acc[ai][bj][m][1]; }
;         }
;     }
	v_pk_fma_f32 v[108:109], v[108:109], v[128:129], v[218:219]
	v_pk_fma_f32 v[110:111], v[110:111], v[130:131], v[220:221]
	v_pk_fma_f32 v[44:45], v[44:45], v[132:133], v[222:223]
	v_pk_fma_f32 v[46:47], v[46:47], v[134:135], v[224:225]
	v_pk_fma_f32 v[104:105], v[104:105], v[128:129], v[226:227]
	v_pk_fma_f32 v[106:107], v[106:107], v[130:131], v[228:229]
	v_pk_fma_f32 v[40:41], v[40:41], v[132:133], v[230:231]
	v_pk_fma_f32 v[42:43], v[42:43], v[134:135], v[232:233]
	global_store_dwordx4 v156, v[108:111], s[26:27] nt
	global_store_dwordx4 v156, v[44:47], s[26:27] offset:512 nt
	global_store_dwordx4 v157, v[104:107], s[26:27] nt
	global_store_dwordx4 v157, v[40:43], s[26:27] offset:512 nt
	s_add_u32 s26, s26, 0x10000
	s_addc_u32 s27, s27, 0
	global_load_dwordx4 v[218:221], v156, s[68:69]
	global_load_dwordx4 v[222:225], v156, s[68:69] offset:512
	global_load_dwordx4 v[226:229], v157, s[68:69]
	global_load_dwordx4 v[230:233], v157, s[68:69] offset:512
	s_add_u32 s68, s68, 0x10000
	s_addc_u32 s69, s69, 0
	ds_write_b128 v154, v[92:95]
	ds_write_b128 v154, v[88:91] offset:16
	ds_read_b128 v[92:95], v155
	ds_read_b128 v[88:91], v155 offset:1152
	ds_write_b128 v154, v[28:31]
	ds_write_b128 v154, v[24:27] offset:16
	ds_read_b128 v[28:31], v155
	ds_read_b128 v[24:27], v155 offset:1152
	s_waitcnt vmcnt(16) lgkmcnt(8)
	v_pk_fma_f32 v[100:101], v[100:101], v[128:129], v[180:181]
	v_pk_fma_f32 v[102:103], v[102:103], v[130:131], v[182:183]
	v_pk_fma_f32 v[36:37], v[36:37], v[132:133], v[184:185]
	v_pk_fma_f32 v[38:39], v[38:39], v[134:135], v[186:187]
	v_pk_fma_f32 v[96:97], v[96:97], v[128:129], v[188:189]
	v_pk_fma_f32 v[98:99], v[98:99], v[130:131], v[190:191]
	v_pk_fma_f32 v[32:33], v[32:33], v[132:133], v[192:193]
	v_pk_fma_f32 v[34:35], v[34:35], v[134:135], v[194:195]
	global_store_dwordx4 v156, v[100:103], s[26:27] nt
	global_store_dwordx4 v156, v[36:39], s[26:27] offset:512 nt
	global_store_dwordx4 v157, v[96:99], s[26:27] nt
	global_store_dwordx4 v157, v[32:35], s[26:27] offset:512 nt
	s_add_u32 s26, s26, 0x50000
	s_addc_u32 s27, s27, 0
	global_load_dwordx4 v[180:183], v156, s[68:69]
	global_load_dwordx4 v[184:187], v156, s[68:69] offset:512
	global_load_dwordx4 v[188:191], v157, s[68:69]
	global_load_dwordx4 v[192:195], v157, s[68:69] offset:512
	s_add_u32 s68, s68, 0x10000
	s_addc_u32 s69, s69, 0
	ds_write_b128 v154, v[84:87]
	ds_write_b128 v154, v[80:83] offset:16
	ds_read_b128 v[84:87], v155
	ds_read_b128 v[80:83], v155 offset:1152
	ds_write_b128 v154, v[20:23]
	ds_write_b128 v154, v[16:19] offset:16
	ds_read_b128 v[20:23], v155
	ds_read_b128 v[16:19], v155 offset:1152
	s_waitcnt vmcnt(16) lgkmcnt(8)
	v_pk_fma_f32 v[92:93], v[92:93], v[128:129], v[196:197]
	v_pk_fma_f32 v[94:95], v[94:95], v[130:131], v[198:199]
	v_pk_fma_f32 v[28:29], v[28:29], v[132:133], v[200:201]
	v_pk_fma_f32 v[30:31], v[30:31], v[134:135], v[202:203]
	v_pk_fma_f32 v[88:89], v[88:89], v[128:129], v[204:205]
	v_pk_fma_f32 v[90:91], v[90:91], v[130:131], v[206:207]
	v_pk_fma_f32 v[24:25], v[24:25], v[132:133], v[214:215]
	v_pk_fma_f32 v[26:27], v[26:27], v[134:135], v[216:217]
	global_store_dwordx4 v156, v[92:95], s[26:27] nt
	global_store_dwordx4 v156, v[28:31], s[26:27] offset:512 nt
	global_store_dwordx4 v157, v[88:91], s[26:27] nt
	global_store_dwordx4 v157, v[24:27], s[26:27] offset:512 nt
	s_add_u32 s26, s26, 0x10000
	s_addc_u32 s27, s27, 0
	global_load_dwordx4 v[196:199], v156, s[68:69]
	global_load_dwordx4 v[200:203], v156, s[68:69] offset:512
	global_load_dwordx4 v[204:207], v157, s[68:69]
	global_load_dwordx4 v[214:217], v157, s[68:69] offset:512
	ds_write_b128 v154, v[76:79]
	ds_write_b128 v154, v[72:75] offset:16
	ds_read_b128 v[76:79], v155
	ds_read_b128 v[72:75], v155 offset:1152
	ds_write_b128 v154, v[12:15]
	ds_write_b128 v154, v[8:11] offset:16
	ds_read_b128 v[12:15], v155
	ds_read_b128 v[8:11], v155 offset:1152
	s_waitcnt vmcnt(16) lgkmcnt(8)
	v_pk_fma_f32 v[84:85], v[84:85], v[128:129], v[218:219]
	v_pk_fma_f32 v[86:87], v[86:87], v[130:131], v[220:221]
	v_pk_fma_f32 v[20:21], v[20:21], v[132:133], v[222:223]
	v_pk_fma_f32 v[22:23], v[22:23], v[134:135], v[224:225]
	v_pk_fma_f32 v[80:81], v[80:81], v[128:129], v[226:227]
	v_pk_fma_f32 v[82:83], v[82:83], v[130:131], v[228:229]
	v_pk_fma_f32 v[16:17], v[16:17], v[132:133], v[230:231]
	v_pk_fma_f32 v[18:19], v[18:19], v[134:135], v[232:233]
	global_store_dwordx4 v156, v[84:87], s[26:27] nt
	global_store_dwordx4 v156, v[20:23], s[26:27] offset:512 nt
	global_store_dwordx4 v157, v[80:83], s[26:27] nt
	global_store_dwordx4 v157, v[16:19], s[26:27] offset:512 nt
	s_add_u32 s26, s26, 0x10000
	s_addc_u32 s27, s27, 0
	ds_write_b128 v154, v[68:71]
	ds_write_b128 v154, v[64:67] offset:16
	ds_read_b128 v[68:71], v155
	ds_read_b128 v[64:67], v155 offset:1152
	ds_write_b128 v154, v[4:7]
	ds_write_b128 v154, v[0:3] offset:16
	ds_read_b128 v[4:7], v155
	ds_read_b128 v[0:3], v155 offset:1152
	s_waitcnt vmcnt(12) lgkmcnt(8)
	v_pk_fma_f32 v[76:77], v[76:77], v[128:129], v[180:181]
	v_pk_fma_f32 v[78:79], v[78:79], v[130:131], v[182:183]
	v_pk_fma_f32 v[12:13], v[12:13], v[132:133], v[184:185]
	v_pk_fma_f32 v[14:15], v[14:15], v[134:135], v[186:187]
	v_pk_fma_f32 v[72:73], v[72:73], v[128:129], v[188:189]
	v_pk_fma_f32 v[74:75], v[74:75], v[130:131], v[190:191]
	v_pk_fma_f32 v[8:9], v[8:9], v[132:133], v[192:193]
	v_pk_fma_f32 v[10:11], v[10:11], v[134:135], v[194:195]
	global_store_dwordx4 v156, v[76:79], s[26:27] nt
	global_store_dwordx4 v156, v[12:15], s[26:27] offset:512 nt
	global_store_dwordx4 v157, v[72:75], s[26:27] nt
	global_store_dwordx4 v157, v[8:11], s[26:27] offset:512 nt
	s_add_u32 s26, s26, 0x10000
	s_addc_u32 s27, s27, 0
	s_waitcnt vmcnt(8) lgkmcnt(0)
	v_pk_fma_f32 v[68:69], v[68:69], v[128:129], v[196:197]
	v_pk_fma_f32 v[70:71], v[70:71], v[130:131], v[198:199]
	v_pk_fma_f32 v[4:5], v[4:5], v[132:133], v[200:201]
	v_pk_fma_f32 v[6:7], v[6:7], v[134:135], v[202:203]
	v_pk_fma_f32 v[64:65], v[64:65], v[128:129], v[204:205]
	v_pk_fma_f32 v[66:67], v[66:67], v[130:131], v[206:207]
	v_pk_fma_f32 v[0:1], v[0:1], v[132:133], v[214:215]
	v_pk_fma_f32 v[2:3], v[2:3], v[134:135], v[216:217]
	global_store_dwordx4 v156, v[68:71], s[26:27] nt
	global_store_dwordx4 v156, v[4:7], s[26:27] offset:512 nt
	global_store_dwordx4 v157, v[64:67], s[26:27] nt
	global_store_dwordx4 v157, v[0:3], s[26:27] offset:512 nt
	s_nop 0
	s_mov_b64 s[26:27], -1
	s_and_b64 vcc, exec, s[4:5]
	s_cbranch_vccnz .LBB0_685
	s_andn2_b64 vcc, exec, s[60:61]
	s_cbranch_vccnz .LBB0_684
	s_barrier
	s_branch .LBB0_684

; DI unsigned pk2(float lo, float hi) { f32x2 v = {lo, hi}; bf16x2_t b = __builtin_convertvector(v, bf16x2_t); return __builtin_bit_cast(unsigned, b); }
;     DI void operator()(const f32x4 (&acc)[2][2][4][2], const Unit& u, int wr, int wc, int fr, int fq) const {
;         const int row0 = u.pm * BM + wr * 64 + fr, col0 = u.pn * BM + wc * 32 + 8 * fq;
; #pragma unroll
;         for (int ai = 0; ai < 2; ++ai)
; #pragma unroll
;             for (int m = 0; m < 4; ++m) { bf16_t* rowp = O + (size_t)(row0 + ai * HALF + m * 16) * ldc + col0;
; #pragma unroll
;                 for (int bj = 0; bj < 2; ++bj) { f32x4 v0 = acc[ai][bj][m][0], v1 = acc[ai][bj][m][1];
;                     if (act) {
; #pragma unroll
;                         for (int q = 0; q < 4; ++q) { float a = fmaxf(v0[q], 0.f), b = fmaxf(v1[q], 0.f); v0[q] = a * a; v1[q] = b * b; } }
;                     u32x4 w; w.x = pk2(v0[0], v0[1]); w.y = pk2(v0[2], v0[3]); w.z = pk2(v1[0], v1[1]); w.w = pk2(v1[2], v1[3]);
;                     *(u32x4*)(rowp + bj * HALF) = w; } }
;     }
.LBB0_764:
	v_and_b32_e32 v192, 15, v142
	v_bfe_u32 v193, v152, 3, 2
	v_lshl_add_u32 v192, v193, 4, v192
	v_lshrrev_b32_e32 v193, 4, v192
	v_and_b32_e32 v194, 3, v192
	v_lshl_add_u32 v193, v193, 2, v194
	v_bfe_u32 v194, v192, 2, 2
	v_lshl_add_u32 v195, v194, 4, v193
	v_lshlrev_b32_e32 v195, 2, v195
	v_and_b32_e32 v196, 0xfffffff0, v142
	v_add_u32_e32 v196, v196, v193
	v_lshl_add_u32 v196, s84, 8, v196
	v_and_b32_e32 v197, 0xffffffe0, v152
	v_lshl_add_u32 v197, v194, 3, v197
	v_lshl_add_u32 v197, s85, 8, v197
	v_mul_lo_u32 v196, v196, s70
	v_add_lshl_u32 v196, v196, v197, 1
	s_lshl_b32 s26, s70, 5
	s_mul_i32 s27, s26, 5
	s_and_b64 vcc, exec, s[46:47]
	s_cbranch_vccz .Lepistore_noact
	v_max_f32_e32 v120, 0, v120
	v_max_f32_e32 v121, 0, v121
	v_max_f32_e32 v122, 0, v122
	v_max_f32_e32 v123, 0, v123
	v_max_f32_e32 v124, 0, v124
	v_max_f32_e32 v125, 0, v125
	v_max_f32_e32 v126, 0, v126
	v_max_f32_e32 v127, 0, v127
	v_pk_mul_f32 v[120:121], v[120:121], v[120:121]
	v_pk_mul_f32 v[122:123], v[122:123], v[122:123]
	v_pk_mul_f32 v[124:125], v[124:125], v[124:125]
	v_pk_mul_f32 v[126:127], v[126:127], v[126:127]
	v_cvt_pk_bf16_f32 v120, v120, v121
	v_cvt_pk_bf16_f32 v121, v122, v123
	v_cvt_pk_bf16_f32 v122, v124, v125
	v_cvt_pk_bf16_f32 v123, v126, v127
	ds_bpermute_b32 v176, v195, v120
	ds_bpermute_b32 v177, v195, v121
	ds_bpermute_b32 v178, v195, v122
	ds_bpermute_b32 v179, v195, v123
	v_max_f32_e32 v116, 0, v116
	v_max_f32_e32 v117, 0, v117
	v_max_f32_e32 v118, 0, v118
	v_max_f32_e32 v119, 0, v119
	v_max_f32_e32 v112, 0, v112
	v_max_f32_e32 v113, 0, v113
	v_max_f32_e32 v114, 0, v114
	v_max_f32_e32 v115, 0, v115
	v_pk_mul_f32 v[116:117], v[116:117], v[116:117]
	v_pk_mul_f32 v[118:119], v[118:119], v[118:119]
	v_pk_mul_f32 v[112:113], v[112:113], v[112:113]
	v_pk_mul_f32 v[114:115], v[114:115], v[114:115]
	v_cvt_pk_bf16_f32 v116, v116, v117
	v_cvt_pk_bf16_f32 v117, v118, v119
	v_cvt_pk_bf16_f32 v118, v112, v113
	v_cvt_pk_bf16_f32 v119, v114, v115
	ds_bpermute_b32 v180, v195, v116
	ds_bpermute_b32 v181, v195, v117
	ds_bpermute_b32 v182, v195, v118
	ds_bpermute_b32 v183, v195, v119
	v_max_f32_e32 v108, 0, v108
	v_max_f32_e32 v109, 0, v109
	v_max_f32_e32 v110, 0, v110
	v_max_f32_e32 v111, 0, v111
	v_max_f32_e32 v104, 0, v104
	v_max_f32_e32 v105, 0, v105
	v_max_f32_e32 v106, 0, v106
	v_max_f32_e32 v107, 0, v107
	v_pk_mul_f32 v[108:109], v[108:109], v[108:109]
	v_pk_mul_f32 v[110:111], v[110:111], v[110:111]
	v_pk_mul_f32 v[104:105], v[104:105], v[104:105]
	v_pk_mul_f32 v[106:107], v[106:107], v[106:107]
	v_cvt_pk_bf16_f32 v108, v108, v109
	v_cvt_pk_bf16_f32 v109, v110, v111
	v_cvt_pk_bf16_f32 v110, v104, v105
	v_cvt_pk_bf16_f32 v111, v106, v107
	s_waitcnt lgkmcnt(4)
	global_store_dwordx4 v196, v[176:179], s[44:45] nt
	ds_bpermute_b32 v184, v195, v108
	ds_bpermute_b32 v185, v195, v109
	ds_bpermute_b32 v186, v195, v110
	ds_bpermute_b32 v187, v195, v111
	v_max_f32_e32 v100, 0, v100
	v_max_f32_e32 v101, 0, v101
	v_max_f32_e32 v102, 0, v102
	v_max_f32_e32 v103, 0, v103
	v_max_f32_e32 v96, 0, v96
	v_max_f32_e32 v97, 0, v97
	v_max_f32_e32 v98, 0, v98
	v_max_f32_e32 v99, 0, v99
	v_pk_mul_f32 v[100:101], v[100:101], v[100:101]
	v_pk_mul_f32 v[102:103], v[102:103], v[102:103]
	v_pk_mul_f32 v[96:97], v[96:97], v[96:97]
	v_pk_mul_f32 v[98:99], v[98:99], v[98:99]
	v_cvt_pk_bf16_f32 v100, v100, v101
	v_cvt_pk_bf16_f32 v101, v102, v103
	v_cvt_pk_bf16_f32 v102, v96, v97
	v_cvt_pk_bf16_f32 v103, v98, v99
	s_waitcnt lgkmcnt(4)
	global_store_dwordx4 v196, v[180:183], s[44:45] offset:256 nt
	v_add_u32_e32 v196, s26, v196
	ds_bpermute_b32 v188, v195, v100
	ds_bpermute_b32 v189, v195, v101
	ds_bpermute_b32 v190, v195, v102
	ds_bpermute_b32 v191, v195, v103
	v_max_f32_e32 v92, 0, v92
	v_max_f32_e32 v93, 0, v93
	v_max_f32_e32 v94, 0, v94
	v_max_f32_e32 v95, 0, v95
	v_max_f32_e32 v88, 0, v88
	v_max_f32_e32 v89, 0, v89
	v_max_f32_e32 v90, 0, v90
	v_max_f32_e32 v91, 0, v91
	v_pk_mul_f32 v[92:93], v[92:93], v[92:93]
	v_pk_mul_f32 v[94:95], v[94:95], v[94:95]
	v_pk_mul_f32 v[88:89], v[88:89], v[88:89]
	v_pk_mul_f32 v[90:91], v[90:91], v[90:91]
	v_cvt_pk_bf16_f32 v92, v92, v93
	v_cvt_pk_bf16_f32 v93, v94, v95
	v_cvt_pk_bf16_f32 v94, v88, v89
	v_cvt_pk_bf16_f32 v95, v90, v91
	s_waitcnt lgkmcnt(4)
	global_store_dwordx4 v196, v[184:187], s[44:45] nt
	ds_bpermute_b32 v176, v195, v92
	ds_bpermute_b32 v177, v195, v93
	ds_bpermute_b32 v178, v195, v94
	ds_bpermute_b32 v179, v195, v95
	v_max_f32_e32 v84, 0, v84
	v_max_f32_e32 v85, 0, v85
	v_max_f32_e32 v86, 0, v86
	v_max_f32_e32 v87, 0, v87
	v_max_f32_e32 v80, 0, v80
	v_max_f32_e32 v81, 0, v81
	v_max_f32_e32 v82, 0, v82
	v_max_f32_e32 v83, 0, v83
	v_pk_mul_f32 v[84:85], v[84:85], v[84:85]
	v_pk_mul_f32 v[86:87], v[86:87], v[86:87]
	v_pk_mul_f32 v[80:81], v[80:81], v[80:81]
	v_pk_mul_f32 v[82:83], v[82:83], v[82:83]
	v_cvt_pk_bf16_f32 v84, v84, v85
	v_cvt_pk_bf16_f32 v85, v86, v87
	v_cvt_pk_bf16_f32 v86, v80, v81
	v_cvt_pk_bf16_f32 v87, v82, v83
	s_waitcnt lgkmcnt(4)
	global_store_dwordx4 v196, v[188:191], s[44:45] offset:256 nt
	v_add_u32_e32 v196, s26, v196
	ds_bpermute_b32 v180, v195, v84
	ds_bpermute_b32 v181, v195, v85
	ds_bpermute_b32 v182, v195, v86
	ds_bpermute_b32 v183, v195, v87
	v_max_f32_e32 v76, 0, v76
	v_max_f32_e32 v77, 0, v77
	v_max_f32_e32 v78, 0, v78
	v_max_f32_e32 v79, 0, v79
	v_max_f32_e32 v72, 0, v72
	v_max_f32_e32 v73, 0, v73
	v_max_f32_e32 v74, 0, v74
	v_max_f32_e32 v75, 0, v75
	v_pk_mul_f32 v[76:77], v[76:77], v[76:77]
	v_pk_mul_f32 v[78:79], v[78:79], v[78:79]
	v_pk_mul_f32 v[72:73], v[72:73], v[72:73]
	v_pk_mul_f32 v[74:75], v[74:75], v[74:75]
	v_cvt_pk_bf16_f32 v76, v76, v77
	v_cvt_pk_bf16_f32 v77, v78, v79
	v_cvt_pk_bf16_f32 v78, v72, v73
	v_cvt_pk_bf16_f32 v79, v74, v75
	s_waitcnt lgkmcnt(4)
; DI unsigned pk2(float lo, float hi) { f32x2 v = {lo, hi}; bf16x2_t b = __builtin_convertvector(v, bf16x2_t); return __builtin_bit_cast(unsigned, b); }
;     DI void operator()(const f32x4 (&acc)[2][2][4][2], const Unit& u, int wr, int wc, int fr, int fq) const {
;         const int row0 = u.pm * BM + wr * 64 + fr, col0 = u.pn * BM + wc * 32 + 8 * fq;
; #pragma unroll
;         for (int ai = 0; ai < 2; ++ai)
; #pragma unroll
;             for (int m = 0; m < 4; ++m) { bf16_t* rowp = O + (size_t)(row0 + ai * HALF + m * 16) * ldc + col0;
; #pragma unroll
;                 for (int bj = 0; bj < 2; ++bj) { f32x4 v0 = acc[ai][bj][m][0], v1 = acc[ai][bj][m][1];
;                     if (act) {
; #pragma unroll
;                         for (int q = 0; q < 4; ++q) { float a = fmaxf(v0[q], 0.f), b = fmaxf(v1[q], 0.f); v0[q] = a * a; v1[q] = b * b; } }
;                     u32x4 w; w.x = pk2(v0[0], v0[1]); w.y = pk2(v0[2], v0[3]); w.z = pk2(v1[0], v1[1]); w.w = pk2(v1[2], v1[3]);
;                     *(u32x4*)(rowp + bj * HALF) = w; } }
;     }
	global_store_dwordx4 v196, v[176:179], s[44:45] nt
	ds_bpermute_b32 v184, v195, v76
	ds_bpermute_b32 v185, v195, v77
	ds_bpermute_b32 v186, v195, v78
	ds_bpermute_b32 v187, v195, v79
	v_max_f32_e32 v68, 0, v68
	v_max_f32_e32 v69, 0, v69
	v_max_f32_e32 v70, 0, v70
	v_max_f32_e32 v71, 0, v71
	v_max_f32_e32 v64, 0, v64
	v_max_f32_e32 v65, 0, v65
	v_max_f32_e32 v66, 0, v66
	v_max_f32_e32 v67, 0, v67
	v_pk_mul_f32 v[68:69], v[68:69], v[68:69]
	v_pk_mul_f32 v[70:71], v[70:71], v[70:71]
	v_pk_mul_f32 v[64:65], v[64:65], v[64:65]
	v_pk_mul_f32 v[66:67], v[66:67], v[66:67]
	v_cvt_pk_bf16_f32 v68, v68, v69
	v_cvt_pk_bf16_f32 v69, v70, v71
	v_cvt_pk_bf16_f32 v70, v64, v65
	v_cvt_pk_bf16_f32 v71, v66, v67
	s_waitcnt lgkmcnt(4)
	global_store_dwordx4 v196, v[180:183], s[44:45] offset:256 nt
	v_add_u32_e32 v196, s26, v196
	ds_bpermute_b32 v188, v195, v68
	ds_bpermute_b32 v189, v195, v69
	ds_bpermute_b32 v190, v195, v70
	ds_bpermute_b32 v191, v195, v71
	v_max_f32_e32 v60, 0, v60
	v_max_f32_e32 v61, 0, v61
	v_max_f32_e32 v62, 0, v62
	v_max_f32_e32 v63, 0, v63
	v_max_f32_e32 v56, 0, v56
	v_max_f32_e32 v57, 0, v57
	v_max_f32_e32 v58, 0, v58
	v_max_f32_e32 v59, 0, v59
	v_pk_mul_f32 v[60:61], v[60:61], v[60:61]
	v_pk_mul_f32 v[62:63], v[62:63], v[62:63]
	v_pk_mul_f32 v[56:57], v[56:57], v[56:57]
	v_pk_mul_f32 v[58:59], v[58:59], v[58:59]
	v_cvt_pk_bf16_f32 v60, v60, v61
	v_cvt_pk_bf16_f32 v61, v62, v63
	v_cvt_pk_bf16_f32 v62, v56, v57
	v_cvt_pk_bf16_f32 v63, v58, v59
	s_waitcnt lgkmcnt(4)
	global_store_dwordx4 v196, v[184:187], s[44:45] nt
	ds_bpermute_b32 v176, v195, v60
	ds_bpermute_b32 v177, v195, v61
	ds_bpermute_b32 v178, v195, v62
	ds_bpermute_b32 v179, v195, v63
	v_max_f32_e32 v52, 0, v52
	v_max_f32_e32 v53, 0, v53
	v_max_f32_e32 v54, 0, v54
	v_max_f32_e32 v55, 0, v55
	v_max_f32_e32 v48, 0, v48
	v_max_f32_e32 v49, 0, v49
	v_max_f32_e32 v50, 0, v50
	v_max_f32_e32 v51, 0, v51
	v_pk_mul_f32 v[52:53], v[52:53], v[52:53]
	v_pk_mul_f32 v[54:55], v[54:55], v[54:55]
	v_pk_mul_f32 v[48:49], v[48:49], v[48:49]
	v_pk_mul_f32 v[50:51], v[50:51], v[50:51]
	v_cvt_pk_bf16_f32 v52, v52, v53
	v_cvt_pk_bf16_f32 v53, v54, v55
	v_cvt_pk_bf16_f32 v54, v48, v49
	v_cvt_pk_bf16_f32 v55, v50, v51
	s_waitcnt lgkmcnt(4)
	global_store_dwordx4 v196, v[188:191], s[44:45] offset:256 nt
	v_add_u32_e32 v196, s27, v196
	ds_bpermute_b32 v180, v195, v52
	ds_bpermute_b32 v181, v195, v53
	ds_bpermute_b32 v182, v195, v54
	ds_bpermute_b32 v183, v195, v55
	v_max_f32_e32 v44, 0, v44
	v_max_f32_e32 v45, 0, v45
	v_max_f32_e32 v46, 0, v46
	v_max_f32_e32 v47, 0, v47
	v_max_f32_e32 v40, 0, v40
	v_max_f32_e32 v41, 0, v41
	v_max_f32_e32 v42, 0, v42
	v_max_f32_e32 v43, 0, v43
	v_pk_mul_f32 v[44:45], v[44:45], v[44:45]
	v_pk_mul_f32 v[46:47], v[46:47], v[46:47]
	v_pk_mul_f32 v[40:41], v[40:41], v[40:41]
	v_pk_mul_f32 v[42:43], v[42:43], v[42:43]
	v_cvt_pk_bf16_f32 v44, v44, v45
	v_cvt_pk_bf16_f32 v45, v46, v47
	v_cvt_pk_bf16_f32 v46, v40, v41
	v_cvt_pk_bf16_f32 v47, v42, v43
	s_waitcnt lgkmcnt(4)
	global_store_dwordx4 v196, v[176:179], s[44:45] nt
	ds_bpermute_b32 v184, v195, v44
	ds_bpermute_b32 v185, v195, v45
	ds_bpermute_b32 v186, v195, v46
	ds_bpermute_b32 v187, v195, v47
	v_max_f32_e32 v36, 0, v36
	v_max_f32_e32 v37, 0, v37
	v_max_f32_e32 v38, 0, v38
	v_max_f32_e32 v39, 0, v39
	v_max_f32_e32 v32, 0, v32
	v_max_f32_e32 v33, 0, v33
	v_max_f32_e32 v34, 0, v34
	v_max_f32_e32 v35, 0, v35
	v_pk_mul_f32 v[36:37], v[36:37], v[36:37]
	v_pk_mul_f32 v[38:39], v[38:39], v[38:39]
	v_pk_mul_f32 v[32:33], v[32:33], v[32:33]
	v_pk_mul_f32 v[34:35], v[34:35], v[34:35]
	v_cvt_pk_bf16_f32 v36, v36, v37
	v_cvt_pk_bf16_f32 v37, v38, v39
	v_cvt_pk_bf16_f32 v38, v32, v33
	v_cvt_pk_bf16_f32 v39, v34, v35
	s_waitcnt lgkmcnt(4)
	global_store_dwordx4 v196, v[180:183], s[44:45] offset:256 nt
	v_add_u32_e32 v196, s26, v196
	ds_bpermute_b32 v188, v195, v36
	ds_bpermute_b32 v189, v195, v37
	ds_bpermute_b32 v190, v195, v38
	ds_bpermute_b32 v191, v195, v39
	v_max_f32_e32 v28, 0, v28
	v_max_f32_e32 v29, 0, v29
	v_max_f32_e32 v30, 0, v30
	v_max_f32_e32 v31, 0, v31
	v_max_f32_e32 v24, 0, v24
	v_max_f32_e32 v25, 0, v25
	v_max_f32_e32 v26, 0, v26
	v_max_f32_e32 v27, 0, v27
	v_pk_mul_f32 v[28:29], v[28:29], v[28:29]
	v_pk_mul_f32 v[30:31], v[30:31], v[30:31]
	v_pk_mul_f32 v[24:25], v[24:25], v[24:25]
	v_pk_mul_f32 v[26:27], v[26:27], v[26:27]
	v_cvt_pk_bf16_f32 v28, v28, v29
	v_cvt_pk_bf16_f32 v29, v30, v31
	v_cvt_pk_bf16_f32 v30, v24, v25
	v_cvt_pk_bf16_f32 v31, v26, v27
	s_waitcnt lgkmcnt(4)
	global_store_dwordx4 v196, v[184:187], s[44:45] nt
	ds_bpermute_b32 v176, v195, v28
	ds_bpermute_b32 v177, v195, v29
	ds_bpermute_b32 v178, v195, v30
	ds_bpermute_b32 v179, v195, v31
	v_max_f32_e32 v20, 0, v20
	v_max_f32_e32 v21, 0, v21
	v_max_f32_e32 v22, 0, v22
	v_max_f32_e32 v23, 0, v23
	v_max_f32_e32 v16, 0, v16
	v_max_f32_e32 v17, 0, v17
	v_max_f32_e32 v18, 0, v18
	v_max_f32_e32 v19, 0, v19
	v_pk_mul_f32 v[20:21], v[20:21], v[20:21]
	v_pk_mul_f32 v[22:23], v[22:23], v[22:23]
	v_pk_mul_f32 v[16:17], v[16:17], v[16:17]
	v_pk_mul_f32 v[18:19], v[18:19], v[18:19]
	v_cvt_pk_bf16_f32 v20, v20, v21
	v_cvt_pk_bf16_f32 v21, v22, v23
	v_cvt_pk_bf16_f32 v22, v16, v17
	v_cvt_pk_bf16_f32 v23, v18, v19
	s_waitcnt lgkmcnt(4)
	global_store_dwordx4 v196, v[188:191], s[44:45] offset:256 nt
	v_add_u32_e32 v196, s26, v196
	ds_bpermute_b32 v180, v195, v20
	ds_bpermute_b32 v181, v195, v21
	ds_bpermute_b32 v182, v195, v22
	ds_bpermute_b32 v183, v195, v23
	v_max_f32_e32 v12, 0, v12
	v_max_f32_e32 v13, 0, v13
	v_max_f32_e32 v14, 0, v14
	v_max_f32_e32 v15, 0, v15
	v_max_f32_e32 v8, 0, v8
	v_max_f32_e32 v9, 0, v9
	v_max_f32_e32 v10, 0, v10
	v_max_f32_e32 v11, 0, v11
	v_pk_mul_f32 v[12:13], v[12:13], v[12:13]
	v_pk_mul_f32 v[14:15], v[14:15], v[14:15]
	v_pk_mul_f32 v[8:9], v[8:9], v[8:9]
	v_pk_mul_f32 v[10:11], v[10:11], v[10:11]
	v_cvt_pk_bf16_f32 v12, v12, v13
	v_cvt_pk_bf16_f32 v13, v14, v15
	v_cvt_pk_bf16_f32 v14, v8, v9
	v_cvt_pk_bf16_f32 v15, v10, v11
	s_waitcnt lgkmcnt(4)
	global_store_dwordx4 v196, v[176:179], s[44:45] nt
	ds_bpermute_b32 v184, v195, v12
	ds_bpermute_b32 v185, v195, v13
	ds_bpermute_b32 v186, v195, v14
	ds_bpermute_b32 v187, v195, v15
	v_max_f32_e32 v4, 0, v4
	v_max_f32_e32 v5, 0, v5
	v_max_f32_e32 v6, 0, v6
	v_max_f32_e32 v7, 0, v7
	v_max_f32_e32 v0, 0, v0
	v_max_f32_e32 v1, 0, v1
	v_max_f32_e32 v2, 0, v2
	v_max_f32_e32 v3, 0, v3
	v_pk_mul_f32 v[4:5], v[4:5], v[4:5]
	v_pk_mul_f32 v[6:7], v[6:7], v[6:7]
	v_pk_mul_f32 v[0:1], v[0:1], v[0:1]
	v_pk_mul_f32 v[2:3], v[2:3], v[2:3]
	v_cvt_pk_bf16_f32 v4, v4, v5
	v_cvt_pk_bf16_f32 v5, v6, v7
	v_cvt_pk_bf16_f32 v6, v0, v1
	v_cvt_pk_bf16_f32 v7, v2, v3
	s_waitcnt lgkmcnt(4)
	global_store_dwordx4 v196, v[180:183], s[44:45] offset:256 nt
	v_add_u32_e32 v196, s26, v196
	ds_bpermute_b32 v188, v195, v4
	ds_bpermute_b32 v189, v195, v5
	ds_bpermute_b32 v190, v195, v6
	ds_bpermute_b32 v191, v195, v7
	s_waitcnt lgkmcnt(4)
	global_store_dwordx4 v196, v[184:187], s[44:45] nt
	s_waitcnt lgkmcnt(0)
	global_store_dwordx4 v196, v[188:191], s[44:45] offset:256 nt
	s_branch .Lepistore_tail
; DI unsigned pk2(float lo, float hi) { f32x2 v = {lo, hi}; bf16x2_t b = __builtin_convertvector(v, bf16x2_t); return __builtin_bit_cast(unsigned, b); }
;     DI void operator()(const f32x4 (&acc)[2][2][4][2], const Unit& u, int wr, int wc, int fr, int fq) const {
;     ...
;             for (int m = 0; m < 4; ++m) { bf16_t* rowp = O + (size_t)(row0 + ai * HALF + m * 16) * ldc + col0;
; #pragma unroll
;                 for (int bj = 0; bj < 2; ++bj) { f32x4 v0 = acc[ai][bj][m][0], v1 = acc[ai][bj][m][1];
;                     if (act) {
; #pragma unroll
;                         for (int q = 0; q < 4; ++q) { float a = fmaxf(v0[q], 0.f), b = fmaxf(v1[q], 0.f); v0[q] = a * a; v1[q] = b * b; } }
;                     u32x4 w; w.x = pk2(v0[0], v0[1]); w.y = pk2(v0[2], v0[3]); w.z = pk2(v1[0], v1[1]); w.w = pk2(v1[2], v1[3]);
;                     *(u32x4*)(rowp + bj * HALF) = w; } }
.Lepistore_noact:
	v_cvt_pk_bf16_f32 v120, v120, v121
	v_cvt_pk_bf16_f32 v121, v122, v123
	v_cvt_pk_bf16_f32 v122, v124, v125
	v_cvt_pk_bf16_f32 v123, v126, v127
	ds_bpermute_b32 v176, v195, v120
	ds_bpermute_b32 v177, v195, v121
	ds_bpermute_b32 v178, v195, v122
	ds_bpermute_b32 v179, v195, v123
	v_cvt_pk_bf16_f32 v116, v116, v117
	v_cvt_pk_bf16_f32 v117, v118, v119
	v_cvt_pk_bf16_f32 v118, v112, v113
	v_cvt_pk_bf16_f32 v119, v114, v115
	ds_bpermute_b32 v180, v195, v116
	ds_bpermute_b32 v181, v195, v117
	ds_bpermute_b32 v182, v195, v118
	ds_bpermute_b32 v183, v195, v119
	v_cvt_pk_bf16_f32 v108, v108, v109
	v_cvt_pk_bf16_f32 v109, v110, v111
	v_cvt_pk_bf16_f32 v110, v104, v105
	v_cvt_pk_bf16_f32 v111, v106, v107
	s_waitcnt lgkmcnt(4)
	global_store_dwordx4 v196, v[176:179], s[44:45] nt
	ds_bpermute_b32 v184, v195, v108
	ds_bpermute_b32 v185, v195, v109
	ds_bpermute_b32 v186, v195, v110
	ds_bpermute_b32 v187, v195, v111
	v_cvt_pk_bf16_f32 v100, v100, v101
	v_cvt_pk_bf16_f32 v101, v102, v103
	v_cvt_pk_bf16_f32 v102, v96, v97
	v_cvt_pk_bf16_f32 v103, v98, v99
	s_waitcnt lgkmcnt(4)
	global_store_dwordx4 v196, v[180:183], s[44:45] offset:256 nt
	v_add_u32_e32 v196, s26, v196
	ds_bpermute_b32 v188, v195, v100
	ds_bpermute_b32 v189, v195, v101
	ds_bpermute_b32 v190, v195, v102
	ds_bpermute_b32 v191, v195, v103
	v_cvt_pk_bf16_f32 v92, v92, v93
	v_cvt_pk_bf16_f32 v93, v94, v95
	v_cvt_pk_bf16_f32 v94, v88, v89
	v_cvt_pk_bf16_f32 v95, v90, v91
	s_waitcnt lgkmcnt(4)
	global_store_dwordx4 v196, v[184:187], s[44:45] nt
	ds_bpermute_b32 v176, v195, v92
	ds_bpermute_b32 v177, v195, v93
	ds_bpermute_b32 v178, v195, v94
	ds_bpermute_b32 v179, v195, v95
	v_cvt_pk_bf16_f32 v84, v84, v85
	v_cvt_pk_bf16_f32 v85, v86, v87
	v_cvt_pk_bf16_f32 v86, v80, v81
	v_cvt_pk_bf16_f32 v87, v82, v83
	s_waitcnt lgkmcnt(4)
	global_store_dwordx4 v196, v[188:191], s[44:45] offset:256 nt
	v_add_u32_e32 v196, s26, v196
	ds_bpermute_b32 v180, v195, v84
	ds_bpermute_b32 v181, v195, v85
	ds_bpermute_b32 v182, v195, v86
	ds_bpermute_b32 v183, v195, v87
	v_cvt_pk_bf16_f32 v76, v76, v77
	v_cvt_pk_bf16_f32 v77, v78, v79
	v_cvt_pk_bf16_f32 v78, v72, v73
	v_cvt_pk_bf16_f32 v79, v74, v75
	s_waitcnt lgkmcnt(4)
	global_store_dwordx4 v196, v[176:179], s[44:45] nt
	ds_bpermute_b32 v184, v195, v76
	ds_bpermute_b32 v185, v195, v77
	ds_bpermute_b32 v186, v195, v78
	ds_bpermute_b32 v187, v195, v79
	v_cvt_pk_bf16_f32 v68, v68, v69
	v_cvt_pk_bf16_f32 v69, v70, v71
	v_cvt_pk_bf16_f32 v70, v64, v65
	v_cvt_pk_bf16_f32 v71, v66, v67
	s_waitcnt lgkmcnt(4)
	global_store_dwordx4 v196, v[180:183], s[44:45] offset:256 nt
	v_add_u32_e32 v196, s26, v196
	ds_bpermute_b32 v188, v195, v68
	ds_bpermute_b32 v189, v195, v69
	ds_bpermute_b32 v190, v195, v70
	ds_bpermute_b32 v191, v195, v71
	v_cvt_pk_bf16_f32 v60, v60, v61
	v_cvt_pk_bf16_f32 v61, v62, v63
	v_cvt_pk_bf16_f32 v62, v56, v57
	v_cvt_pk_bf16_f32 v63, v58, v59
	s_waitcnt lgkmcnt(4)
	global_store_dwordx4 v196, v[184:187], s[44:45] nt
	ds_bpermute_b32 v176, v195, v60
	ds_bpermute_b32 v177, v195, v61
	ds_bpermute_b32 v178, v195, v62
	ds_bpermute_b32 v179, v195, v63
	v_cvt_pk_bf16_f32 v52, v52, v53
	v_cvt_pk_bf16_f32 v53, v54, v55
	v_cvt_pk_bf16_f32 v54, v48, v49
	v_cvt_pk_bf16_f32 v55, v50, v51
	s_waitcnt lgkmcnt(4)
	global_store_dwordx4 v196, v[188:191], s[44:45] offset:256 nt
	v_add_u32_e32 v196, s27, v196
	ds_bpermute_b32 v180, v195, v52
	ds_bpermute_b32 v181, v195, v53
	ds_bpermute_b32 v182, v195, v54
	ds_bpermute_b32 v183, v195, v55
	v_cvt_pk_bf16_f32 v44, v44, v45
	v_cvt_pk_bf16_f32 v45, v46, v47
	v_cvt_pk_bf16_f32 v46, v40, v41
	v_cvt_pk_bf16_f32 v47, v42, v43
	s_waitcnt lgkmcnt(4)
	global_store_dwordx4 v196, v[176:179], s[44:45] nt
	ds_bpermute_b32 v184, v195, v44
	ds_bpermute_b32 v185, v195, v45
	ds_bpermute_b32 v186, v195, v46
	ds_bpermute_b32 v187, v195, v47
	v_cvt_pk_bf16_f32 v36, v36, v37
	v_cvt_pk_bf16_f32 v37, v38, v39
	v_cvt_pk_bf16_f32 v38, v32, v33
	v_cvt_pk_bf16_f32 v39, v34, v35
	s_waitcnt lgkmcnt(4)
	global_store_dwordx4 v196, v[180:183], s[44:45] offset:256 nt
	v_add_u32_e32 v196, s26, v196
	ds_bpermute_b32 v188, v195, v36
	ds_bpermute_b32 v189, v195, v37
	ds_bpermute_b32 v190, v195, v38
	ds_bpermute_b32 v191, v195, v39
	v_cvt_pk_bf16_f32 v28, v28, v29
	v_cvt_pk_bf16_f32 v29, v30, v31
	v_cvt_pk_bf16_f32 v30, v24, v25
	v_cvt_pk_bf16_f32 v31, v26, v27
	s_waitcnt lgkmcnt(4)
	global_store_dwordx4 v196, v[184:187], s[44:45] nt
	ds_bpermute_b32 v176, v195, v28
	ds_bpermute_b32 v177, v195, v29
	ds_bpermute_b32 v178, v195, v30
	ds_bpermute_b32 v179, v195, v31
	v_cvt_pk_bf16_f32 v20, v20, v21
	v_cvt_pk_bf16_f32 v21, v22, v23
	v_cvt_pk_bf16_f32 v22, v16, v17
	v_cvt_pk_bf16_f32 v23, v18, v19
	s_waitcnt lgkmcnt(4)
	global_store_dwordx4 v196, v[188:191], s[44:45] offset:256 nt
	v_add_u32_e32 v196, s26, v196
	ds_bpermute_b32 v180, v195, v20
	ds_bpermute_b32 v181, v195, v21
	ds_bpermute_b32 v182, v195, v22
	ds_bpermute_b32 v183, v195, v23
	v_cvt_pk_bf16_f32 v12, v12, v13
	v_cvt_pk_bf16_f32 v13, v14, v15
	v_cvt_pk_bf16_f32 v14, v8, v9
	v_cvt_pk_bf16_f32 v15, v10, v11
	s_waitcnt lgkmcnt(4)
	global_store_dwordx4 v196, v[176:179], s[44:45] nt
	ds_bpermute_b32 v184, v195, v12
	ds_bpermute_b32 v185, v195, v13
	ds_bpermute_b32 v186, v195, v14
	ds_bpermute_b32 v187, v195, v15
	v_cvt_pk_bf16_f32 v4, v4, v5
	v_cvt_pk_bf16_f32 v5, v6, v7
	v_cvt_pk_bf16_f32 v6, v0, v1
	v_cvt_pk_bf16_f32 v7, v2, v3
	s_waitcnt lgkmcnt(4)
	global_store_dwordx4 v196, v[180:183], s[44:45] offset:256 nt
	v_add_u32_e32 v196, s26, v196
	ds_bpermute_b32 v188, v195, v4
	ds_bpermute_b32 v189, v195, v5
	ds_bpermute_b32 v190, v195, v6
	ds_bpermute_b32 v191, v195, v7
	s_waitcnt lgkmcnt(4)
	global_store_dwordx4 v196, v[184:187], s[44:45] nt
	s_waitcnt lgkmcnt(0)
	global_store_dwordx4 v196, v[188:191], s[44:45] offset:256 nt
